# scan v2: packed-f32 S-update and dot, private loop latch for scan waves (no LDS drain before the chunk barrier)
# speedup vs baseline: 1.0174x; 1.0174x over previous
; #define LAS __attribute__((address_space(3)))
; __device__ __forceinline__ float row16_sum(float v) { v += dpp_f<0xB1>(v); v += dpp_f<0x4E>(v); v += dpp_f<0x141>(v); v += dpp_f<0x140>(v); return v; }
; __device__ __forceinline__ void rwkv_scan_unit(LAS unsigned char* lds, const float* Wd, const float* V, const bf16_t* RKKB, float* Yraw, int p, int rg, int tid) {
;     ...
;     for (int c = 0; c < NCH; ++c) {
;         if (wave >= 4) { if (c + 2 < NCH) scan_load_chunk(lds + ((c + 2) % 3) * SCAN_SLOT_B, Wd, V, RKKB, p, rg, (c + 2) * SCAN_CH, tid - 256); }
;         else {
;             LAS const unsigned char* sl = lds + (c % 3) * SCAN_SLOT_B + kq * 16;
;             LAS const unsigned char* vl = lds + (c % 3) * SCAN_SLOT_B + 1280 + rl * 4;
;             float* yo = Yraw + ((size_t)p * SEQ + c * SCAN_CH + kq) * 64 + rg * 16 + rl;
;             f32x4 w = *(LAS const f32x4*)(sl), b = *(LAS const f32x4*)(sl + 256), k = *(LAS const f32x4*)(sl + 512), kk = *(LAS const f32x4*)(sl + 768), r = *(LAS const f32x4*)(sl + 1024);
;             float v = *(LAS const float*)(vl); float yp[16];
; #pragma unroll
;             for (int st = 0; st < SCAN_CH; ++st) {
;                 f32x4 wn = w, bn = b, kn = k, kkn = kk, rn = r; float vn = v;
;                 if (st + 1 < SCAN_CH) { const int o = (st + 1) * SCAN_STEP_B;
;                     wn = *(LAS const f32x4*)(sl + o); bn = *(LAS const f32x4*)(sl + o + 256); kn = *(LAS const f32x4*)(sl + o + 512); kkn = *(LAS const f32x4*)(sl + o + 768); rn = *(LAS const f32x4*)(sl + o + 1024);
;                     vn = *(LAS const float*)(vl + o); }
;                 float sa = (S[0] * kk[0] + S[1] * kk[1]) + (S[2] * kk[2] + S[3] * kk[3]);
;                 const f32x4 kvt = k * v;
;                 sa = -row16_sum(sa);
;                 S = S * w + (b * sa + kvt);
;                 yp[st & 15] = (S[0] * r[0] + S[1] * r[1]) + (S[2] * r[2] + S[3] * r[3]);
;                 if ((st & 15) == 15) yo[(size_t)(st - 15) * 64] = tr16_sum(yp, kq);
;                 w = wn; b = bn; k = kn; kk = kkn; r = rn; v = vn;
;             }
.Lscan_top:
	s_mul_i32 s18, s22, 0xab
	s_bfe_u32 s18, s18, 0x70009
	s_mul_i32 s18, s18, 3
	s_sub_i32 s18, s22, s18
	s_and_b32 s18, s18, 0xff
	s_mul_i32 s18, s18, 0xa800
	s_add_i32 s19, s18, 0xa800
	s_cmp_eq_u32 s19, 0x1f800
	s_cselect_b32 s19, 0, s19
	v_add_u32_e32 v84, s18, v71
	v_add_u32_e32 v83, s18, v72
	v_add_u32_e32 v86, s19, v71
	v_add_u32_e32 v85, s19, v72
	v_lshl_add_u64 v[62:63], v[60:61], 0, s[14:15]
	s_mov_b64 s[20:21], 0x16100000
	v_lshl_add_u64 v[88:89], v[62:63], 0, s[20:21]
	s_mov_b64 s[20:21], 0x16101000
	v_lshl_add_u64 v[90:91], v[62:63], 0, s[20:21]
	s_waitcnt lgkmcnt(6)
	v_pk_mul_f32 v[10:11], v[2:3], v[132:133]
	v_pk_fma_f32 v[10:11], v[4:5], v[134:135], v[10:11]
	v_pk_mul_f32 v[6:7], v[128:129], v[140:141] op_sel_hi:[1,0]
	v_add_f32_e32 v12, v10, v11
	v_pk_mul_f32 v[8:9], v[130:131], v[140:141] op_sel_hi:[1,0]
	v_pk_fma_f32 v[6:7], v[2:3], v[120:121], v[6:7]
	v_add_f32_dpp v12, v12, v12 quad_perm:[1,0,3,2] row_mask:0xf bank_mask:0xf bound_ctrl:1
	v_pk_fma_f32 v[8:9], v[4:5], v[122:123], v[8:9]
	ds_read_b128 v[180:183], v84 offset:3456
	v_add_f32_dpp v12, v12, v12 quad_perm:[2,3,0,1] row_mask:0xf bank_mask:0xf bound_ctrl:1
	ds_read_b128 v[168:171], v84 offset:2688
	ds_read_b128 v[176:179], v84 offset:3200
	v_add_f32_dpp v12, v12, v12 row_half_mirror row_mask:0xf bank_mask:0xf bound_ctrl:1
	ds_read_b32 v188, v83 offset:3968
	ds_read_b128 v[172:175], v84 offset:2944
	v_add_f32_dpp v12, v12, v12 row_mirror row_mask:0xf bank_mask:0xf bound_ctrl:1
	ds_read_b128 v[184:187], v84 offset:3712
	v_pk_fma_f32 v[2:3], v[124:125], v[12:13], v[6:7] op_sel_hi:[1,0,1] neg_lo:[0,1,0] neg_hi:[0,1,0]
	v_pk_fma_f32 v[4:5], v[126:127], v[12:13], v[8:9] op_sel_hi:[1,0,1] neg_lo:[0,1,0] neg_hi:[0,1,0]
	s_waitcnt lgkmcnt(6)
	v_pk_mul_f32 v[10:11], v[2:3], v[156:157]
	v_pk_fma_f32 v[10:11], v[4:5], v[158:159], v[10:11]
	v_pk_mul_f32 v[14:15], v[2:3], v[136:137]
	v_add_f32_e32 v12, v10, v11
	v_pk_fma_f32 v[14:15], v[4:5], v[138:139], v[14:15]
	v_add_f32_e32 v100, v14, v15
	v_add_f32_dpp v12, v12, v12 quad_perm:[1,0,3,2] row_mask:0xf bank_mask:0xf bound_ctrl:1
	v_pk_mul_f32 v[6:7], v[152:153], v[164:165] op_sel_hi:[1,0]
	v_pk_mul_f32 v[8:9], v[154:155], v[164:165] op_sel_hi:[1,0]
	v_add_f32_dpp v12, v12, v12 quad_perm:[2,3,0,1] row_mask:0xf bank_mask:0xf bound_ctrl:1
	v_pk_fma_f32 v[6:7], v[2:3], v[144:145], v[6:7]
	v_pk_fma_f32 v[8:9], v[4:5], v[146:147], v[8:9]
	v_add_f32_dpp v12, v12, v12 row_half_mirror row_mask:0xf bank_mask:0xf bound_ctrl:1
	ds_read_b128 v[34:37], v84 offset:4800
	ds_read_b128 v[22:25], v84 offset:4032
	v_add_f32_dpp v12, v12, v12 row_mirror row_mask:0xf bank_mask:0xf bound_ctrl:1
	ds_read_b128 v[30:33], v84 offset:4544
	ds_read_b32 v42, v83 offset:5312
	ds_read_b128 v[26:29], v84 offset:4288
	ds_read_b128 v[38:41], v84 offset:5056
	v_pk_fma_f32 v[2:3], v[148:149], v[12:13], v[6:7] op_sel_hi:[1,0,1] neg_lo:[0,1,0] neg_hi:[0,1,0]
	v_pk_fma_f32 v[4:5], v[150:151], v[12:13], v[8:9] op_sel_hi:[1,0,1] neg_lo:[0,1,0] neg_hi:[0,1,0]
	s_waitcnt lgkmcnt(6)
	v_pk_mul_f32 v[10:11], v[2:3], v[180:181]
	v_pk_fma_f32 v[10:11], v[4:5], v[182:183], v[10:11]
	v_pk_mul_f32 v[14:15], v[2:3], v[160:161]
	v_add_f32_e32 v12, v10, v11
	v_pk_fma_f32 v[14:15], v[4:5], v[162:163], v[14:15]
	v_add_f32_e32 v101, v14, v15
	v_add_f32_dpp v12, v12, v12 quad_perm:[1,0,3,2] row_mask:0xf bank_mask:0xf bound_ctrl:1
	v_pk_mul_f32 v[6:7], v[176:177], v[188:189] op_sel_hi:[1,0]
	v_pk_mul_f32 v[8:9], v[178:179], v[188:189] op_sel_hi:[1,0]
	v_add_f32_dpp v12, v12, v12 quad_perm:[2,3,0,1] row_mask:0xf bank_mask:0xf bound_ctrl:1
	v_pk_fma_f32 v[6:7], v[2:3], v[168:169], v[6:7]
	v_pk_fma_f32 v[8:9], v[4:5], v[170:171], v[8:9]
	v_add_f32_dpp v12, v12, v12 row_half_mirror row_mask:0xf bank_mask:0xf bound_ctrl:1
	ds_read_b128 v[132:135], v84 offset:6144
	ds_read_b128 v[120:123], v84 offset:5376
	v_add_f32_dpp v12, v12, v12 row_mirror row_mask:0xf bank_mask:0xf bound_ctrl:1
	ds_read_b128 v[128:131], v84 offset:5888
	ds_read_b32 v140, v83 offset:6656
	ds_read_b128 v[124:127], v84 offset:5632
	ds_read_b128 v[136:139], v84 offset:6400
	v_pk_fma_f32 v[2:3], v[172:173], v[12:13], v[6:7] op_sel_hi:[1,0,1] neg_lo:[0,1,0] neg_hi:[0,1,0]
	v_pk_fma_f32 v[4:5], v[174:175], v[12:13], v[8:9] op_sel_hi:[1,0,1] neg_lo:[0,1,0] neg_hi:[0,1,0]
	s_waitcnt lgkmcnt(6)
	v_pk_mul_f32 v[10:11], v[2:3], v[34:35]
	v_pk_fma_f32 v[10:11], v[4:5], v[36:37], v[10:11]
	v_pk_mul_f32 v[14:15], v[2:3], v[184:185]
	v_add_f32_e32 v12, v10, v11
	v_pk_fma_f32 v[14:15], v[4:5], v[186:187], v[14:15]
	v_add_f32_e32 v102, v14, v15
	v_add_f32_dpp v12, v12, v12 quad_perm:[1,0,3,2] row_mask:0xf bank_mask:0xf bound_ctrl:1
	v_pk_mul_f32 v[6:7], v[30:31], v[42:43] op_sel_hi:[1,0]
	v_pk_mul_f32 v[8:9], v[32:33], v[42:43] op_sel_hi:[1,0]
	v_add_f32_dpp v12, v12, v12 quad_perm:[2,3,0,1] row_mask:0xf bank_mask:0xf bound_ctrl:1
	v_pk_fma_f32 v[6:7], v[2:3], v[22:23], v[6:7]
	v_pk_fma_f32 v[8:9], v[4:5], v[24:25], v[8:9]
	v_add_f32_dpp v12, v12, v12 row_half_mirror row_mask:0xf bank_mask:0xf bound_ctrl:1
	ds_read_b128 v[156:159], v84 offset:7488
	ds_read_b128 v[144:147], v84 offset:6720
	v_add_f32_dpp v12, v12, v12 row_mirror row_mask:0xf bank_mask:0xf bound_ctrl:1
	ds_read_b128 v[152:155], v84 offset:7232
	ds_read_b32 v164, v83 offset:8000
	ds_read_b128 v[148:151], v84 offset:6976
	ds_read_b128 v[160:163], v84 offset:7744
	v_pk_fma_f32 v[2:3], v[26:27], v[12:13], v[6:7] op_sel_hi:[1,0,1] neg_lo:[0,1,0] neg_hi:[0,1,0]
	v_pk_fma_f32 v[4:5], v[28:29], v[12:13], v[8:9] op_sel_hi:[1,0,1] neg_lo:[0,1,0] neg_hi:[0,1,0]
	s_waitcnt lgkmcnt(6)
; #define LAS __attribute__((address_space(3)))
; __device__ __forceinline__ float row16_sum(float v) { v += dpp_f<0xB1>(v); v += dpp_f<0x4E>(v); v += dpp_f<0x141>(v); v += dpp_f<0x140>(v); return v; }
; __device__ __forceinline__ void rwkv_scan_unit(LAS unsigned char* lds, const float* Wd, const float* V, const bf16_t* RKKB, float* Yraw, int p, int rg, int tid) {
;     ...
;             for (int st = 0; st < SCAN_CH; ++st) {
;                 f32x4 wn = w, bn = b, kn = k, kkn = kk, rn = r; float vn = v;
;                 if (st + 1 < SCAN_CH) { const int o = (st + 1) * SCAN_STEP_B;
;                     wn = *(LAS const f32x4*)(sl + o); bn = *(LAS const f32x4*)(sl + o + 256); kn = *(LAS const f32x4*)(sl + o + 512); kkn = *(LAS const f32x4*)(sl + o + 768); rn = *(LAS const f32x4*)(sl + o + 1024);
;                     vn = *(LAS const float*)(vl + o); }
;                 float sa = (S[0] * kk[0] + S[1] * kk[1]) + (S[2] * kk[2] + S[3] * kk[3]);
;                 const f32x4 kvt = k * v;
;                 sa = -row16_sum(sa);
;                 S = S * w + (b * sa + kvt);
;                 yp[st & 15] = (S[0] * r[0] + S[1] * r[1]) + (S[2] * r[2] + S[3] * r[3]);
;                 if ((st & 15) == 15) yo[(size_t)(st - 15) * 64] = tr16_sum(yp, kq);
;                 w = wn; b = bn; k = kn; kk = kkn; r = rn; v = vn;
	v_pk_mul_f32 v[10:11], v[2:3], v[132:133]
	v_pk_fma_f32 v[10:11], v[4:5], v[134:135], v[10:11]
	v_pk_mul_f32 v[14:15], v[2:3], v[38:39]
	v_add_f32_e32 v12, v10, v11
	v_pk_fma_f32 v[14:15], v[4:5], v[40:41], v[14:15]
	v_add_f32_e32 v103, v14, v15
	v_add_f32_dpp v12, v12, v12 quad_perm:[1,0,3,2] row_mask:0xf bank_mask:0xf bound_ctrl:1
	v_pk_mul_f32 v[6:7], v[128:129], v[140:141] op_sel_hi:[1,0]
	v_pk_mul_f32 v[8:9], v[130:131], v[140:141] op_sel_hi:[1,0]
	v_add_f32_dpp v12, v12, v12 quad_perm:[2,3,0,1] row_mask:0xf bank_mask:0xf bound_ctrl:1
	v_pk_fma_f32 v[6:7], v[2:3], v[120:121], v[6:7]
	v_pk_fma_f32 v[8:9], v[4:5], v[122:123], v[8:9]
	v_add_f32_dpp v12, v12, v12 row_half_mirror row_mask:0xf bank_mask:0xf bound_ctrl:1
	ds_read_b128 v[180:183], v84 offset:8832
	ds_read_b128 v[168:171], v84 offset:8064
	v_add_f32_dpp v12, v12, v12 row_mirror row_mask:0xf bank_mask:0xf bound_ctrl:1
	ds_read_b128 v[176:179], v84 offset:8576
	ds_read_b32 v188, v83 offset:9344
	ds_read_b128 v[172:175], v84 offset:8320
	ds_read_b128 v[184:187], v84 offset:9088
	v_pk_fma_f32 v[2:3], v[124:125], v[12:13], v[6:7] op_sel_hi:[1,0,1] neg_lo:[0,1,0] neg_hi:[0,1,0]
	v_pk_fma_f32 v[4:5], v[126:127], v[12:13], v[8:9] op_sel_hi:[1,0,1] neg_lo:[0,1,0] neg_hi:[0,1,0]
	s_waitcnt lgkmcnt(6)
	v_pk_mul_f32 v[10:11], v[2:3], v[156:157]
	v_pk_fma_f32 v[10:11], v[4:5], v[158:159], v[10:11]
	v_pk_mul_f32 v[14:15], v[2:3], v[136:137]
	v_add_f32_e32 v12, v10, v11
	v_pk_fma_f32 v[14:15], v[4:5], v[138:139], v[14:15]
	v_add_f32_e32 v104, v14, v15
	v_add_f32_dpp v12, v12, v12 quad_perm:[1,0,3,2] row_mask:0xf bank_mask:0xf bound_ctrl:1
	v_pk_mul_f32 v[6:7], v[152:153], v[164:165] op_sel_hi:[1,0]
	v_pk_mul_f32 v[8:9], v[154:155], v[164:165] op_sel_hi:[1,0]
	v_add_f32_dpp v12, v12, v12 quad_perm:[2,3,0,1] row_mask:0xf bank_mask:0xf bound_ctrl:1
	v_pk_fma_f32 v[6:7], v[2:3], v[144:145], v[6:7]
	v_pk_fma_f32 v[8:9], v[4:5], v[146:147], v[8:9]
	v_add_f32_dpp v12, v12, v12 row_half_mirror row_mask:0xf bank_mask:0xf bound_ctrl:1
	ds_read_b128 v[34:37], v84 offset:10176
	ds_read_b128 v[22:25], v84 offset:9408
	v_add_f32_dpp v12, v12, v12 row_mirror row_mask:0xf bank_mask:0xf bound_ctrl:1
	ds_read_b128 v[30:33], v84 offset:9920
	ds_read_b32 v42, v83 offset:10688
	ds_read_b128 v[26:29], v84 offset:9664
	ds_read_b128 v[38:41], v84 offset:10432
	v_pk_fma_f32 v[2:3], v[148:149], v[12:13], v[6:7] op_sel_hi:[1,0,1] neg_lo:[0,1,0] neg_hi:[0,1,0]
	v_pk_fma_f32 v[4:5], v[150:151], v[12:13], v[8:9] op_sel_hi:[1,0,1] neg_lo:[0,1,0] neg_hi:[0,1,0]
	s_waitcnt lgkmcnt(6)
	v_pk_mul_f32 v[10:11], v[2:3], v[180:181]
	v_pk_fma_f32 v[10:11], v[4:5], v[182:183], v[10:11]
	v_pk_mul_f32 v[14:15], v[2:3], v[160:161]
	v_add_f32_e32 v12, v10, v11
	v_pk_fma_f32 v[14:15], v[4:5], v[162:163], v[14:15]
	v_add_f32_e32 v105, v14, v15
	v_add_f32_dpp v12, v12, v12 quad_perm:[1,0,3,2] row_mask:0xf bank_mask:0xf bound_ctrl:1
	v_pk_mul_f32 v[6:7], v[176:177], v[188:189] op_sel_hi:[1,0]
	v_pk_mul_f32 v[8:9], v[178:179], v[188:189] op_sel_hi:[1,0]
	v_add_f32_dpp v12, v12, v12 quad_perm:[2,3,0,1] row_mask:0xf bank_mask:0xf bound_ctrl:1
	v_pk_fma_f32 v[6:7], v[2:3], v[168:169], v[6:7]
	v_pk_fma_f32 v[8:9], v[4:5], v[170:171], v[8:9]
	v_add_f32_dpp v12, v12, v12 row_half_mirror row_mask:0xf bank_mask:0xf bound_ctrl:1
	ds_read_b128 v[132:135], v84 offset:11520
	ds_read_b128 v[120:123], v84 offset:10752
	v_add_f32_dpp v12, v12, v12 row_mirror row_mask:0xf bank_mask:0xf bound_ctrl:1
	ds_read_b128 v[128:131], v84 offset:11264
	ds_read_b32 v140, v83 offset:12032
	ds_read_b128 v[124:127], v84 offset:11008
	ds_read_b128 v[136:139], v84 offset:11776
	v_pk_fma_f32 v[2:3], v[172:173], v[12:13], v[6:7] op_sel_hi:[1,0,1] neg_lo:[0,1,0] neg_hi:[0,1,0]
	v_pk_fma_f32 v[4:5], v[174:175], v[12:13], v[8:9] op_sel_hi:[1,0,1] neg_lo:[0,1,0] neg_hi:[0,1,0]
	s_waitcnt lgkmcnt(6)
	v_pk_mul_f32 v[10:11], v[2:3], v[34:35]
	v_pk_fma_f32 v[10:11], v[4:5], v[36:37], v[10:11]
	v_pk_mul_f32 v[14:15], v[2:3], v[184:185]
	v_add_f32_e32 v12, v10, v11
	v_pk_fma_f32 v[14:15], v[4:5], v[186:187], v[14:15]
	v_add_f32_e32 v106, v14, v15
	v_add_f32_dpp v12, v12, v12 quad_perm:[1,0,3,2] row_mask:0xf bank_mask:0xf bound_ctrl:1
	v_pk_mul_f32 v[6:7], v[30:31], v[42:43] op_sel_hi:[1,0]
	v_pk_mul_f32 v[8:9], v[32:33], v[42:43] op_sel_hi:[1,0]
	v_add_f32_dpp v12, v12, v12 quad_perm:[2,3,0,1] row_mask:0xf bank_mask:0xf bound_ctrl:1
	v_pk_fma_f32 v[6:7], v[2:3], v[22:23], v[6:7]
	v_pk_fma_f32 v[8:9], v[4:5], v[24:25], v[8:9]
	v_add_f32_dpp v12, v12, v12 row_half_mirror row_mask:0xf bank_mask:0xf bound_ctrl:1
	ds_read_b128 v[156:159], v84 offset:12864
	ds_read_b128 v[144:147], v84 offset:12096
	v_add_f32_dpp v12, v12, v12 row_mirror row_mask:0xf bank_mask:0xf bound_ctrl:1
	ds_read_b128 v[152:155], v84 offset:12608
	ds_read_b32 v164, v83 offset:13376
	ds_read_b128 v[148:151], v84 offset:12352
	ds_read_b128 v[160:163], v84 offset:13120
	v_pk_fma_f32 v[2:3], v[26:27], v[12:13], v[6:7] op_sel_hi:[1,0,1] neg_lo:[0,1,0] neg_hi:[0,1,0]
	v_pk_fma_f32 v[4:5], v[28:29], v[12:13], v[8:9] op_sel_hi:[1,0,1] neg_lo:[0,1,0] neg_hi:[0,1,0]
	s_waitcnt lgkmcnt(6)
; #define LAS __attribute__((address_space(3)))
; template <int CTRL> __device__ __forceinline__ float dpp_f(float v) { return __int_as_float(__builtin_amdgcn_update_dpp(0, __float_as_int(v), CTRL, 0xf, 0xf, true)); }
; __device__ __forceinline__ float row16_sum(float v) { v += dpp_f<0xB1>(v); v += dpp_f<0x4E>(v); v += dpp_f<0x141>(v); v += dpp_f<0x140>(v); return v; }
; __device__ __forceinline__ float tr16_sum(const float (&p)[16], int kq) {
;     const bool b3 = (kq & 8) != 0, b2 = (kq & 4) != 0, b1 = (kq & 2) != 0, b0 = (kq & 1) != 0;
;     float q[8], r[4], u[2];
; #pragma unroll
;     for (int t = 0; t < 8; ++t) { const float keep = b3 ? p[t + 8] : p[t], send = b3 ? p[t] : p[t + 8]; q[t] = keep + dpp_f<0x140>(send); }
; #pragma unroll
;     for (int t = 0; t < 4; ++t) { const float keep = b2 ? q[t + 4] : q[t], send = b2 ? q[t] : q[t + 4]; r[t] = keep + dpp_f<0x141>(send); }
; #pragma unroll
;     for (int t = 0; t < 2; ++t) { const float keep = b1 ? r[t + 2] : r[t], send = b1 ? r[t] : r[t + 2]; u[t] = keep + dpp_f<0x4E>(send); }
;     const float keep = b0 ? u[1] : u[0], send = b0 ? u[0] : u[1];
;     return keep + dpp_f<0xB1>(send);
; __device__ __forceinline__ void rwkv_scan_unit(LAS unsigned char* lds, const float* Wd, const float* V, const bf16_t* RKKB, float* Yraw, int p, int rg, int tid) {
;     ...
;             for (int st = 0; st < SCAN_CH; ++st) {
;                 f32x4 wn = w, bn = b, kn = k, kkn = kk, rn = r; float vn = v;
;                 if (st + 1 < SCAN_CH) { const int o = (st + 1) * SCAN_STEP_B;
;                     wn = *(LAS const f32x4*)(sl + o); bn = *(LAS const f32x4*)(sl + o + 256); kn = *(LAS const f32x4*)(sl + o + 512); kkn = *(LAS const f32x4*)(sl + o + 768); rn = *(LAS const f32x4*)(sl + o + 1024);
;                     vn = *(LAS const float*)(vl + o); }
;                 float sa = (S[0] * kk[0] + S[1] * kk[1]) + (S[2] * kk[2] + S[3] * kk[3]);
;                 const f32x4 kvt = k * v;
;                 sa = -row16_sum(sa);
;                 S = S * w + (b * sa + kvt);
;                 yp[st & 15] = (S[0] * r[0] + S[1] * r[1]) + (S[2] * r[2] + S[3] * r[3]);
;                 if ((st & 15) == 15) yo[(size_t)(st - 15) * 64] = tr16_sum(yp, kq);
;                 w = wn; b = bn; k = kn; kk = kkn; r = rn; v = vn;
	v_pk_mul_f32 v[10:11], v[2:3], v[132:133]
	v_pk_fma_f32 v[10:11], v[4:5], v[134:135], v[10:11]
	v_pk_mul_f32 v[14:15], v[2:3], v[38:39]
	v_add_f32_e32 v12, v10, v11
	v_pk_fma_f32 v[14:15], v[4:5], v[40:41], v[14:15]
	v_add_f32_e32 v107, v14, v15
	v_add_f32_dpp v12, v12, v12 quad_perm:[1,0,3,2] row_mask:0xf bank_mask:0xf bound_ctrl:1
	v_pk_mul_f32 v[6:7], v[128:129], v[140:141] op_sel_hi:[1,0]
	v_pk_mul_f32 v[8:9], v[130:131], v[140:141] op_sel_hi:[1,0]
	v_add_f32_dpp v12, v12, v12 quad_perm:[2,3,0,1] row_mask:0xf bank_mask:0xf bound_ctrl:1
	v_pk_fma_f32 v[6:7], v[2:3], v[120:121], v[6:7]
	v_pk_fma_f32 v[8:9], v[4:5], v[122:123], v[8:9]
	v_add_f32_dpp v12, v12, v12 row_half_mirror row_mask:0xf bank_mask:0xf bound_ctrl:1
	ds_read_b128 v[180:183], v84 offset:14208
	ds_read_b128 v[168:171], v84 offset:13440
	v_add_f32_dpp v12, v12, v12 row_mirror row_mask:0xf bank_mask:0xf bound_ctrl:1
	ds_read_b128 v[176:179], v84 offset:13952
	ds_read_b32 v188, v83 offset:14720
	ds_read_b128 v[172:175], v84 offset:13696
	ds_read_b128 v[184:187], v84 offset:14464
	v_pk_fma_f32 v[2:3], v[124:125], v[12:13], v[6:7] op_sel_hi:[1,0,1] neg_lo:[0,1,0] neg_hi:[0,1,0]
	v_pk_fma_f32 v[4:5], v[126:127], v[12:13], v[8:9] op_sel_hi:[1,0,1] neg_lo:[0,1,0] neg_hi:[0,1,0]
	s_waitcnt lgkmcnt(6)
	v_pk_mul_f32 v[10:11], v[2:3], v[156:157]
	v_pk_fma_f32 v[10:11], v[4:5], v[158:159], v[10:11]
	v_pk_mul_f32 v[14:15], v[2:3], v[136:137]
	v_add_f32_e32 v12, v10, v11
	v_pk_fma_f32 v[14:15], v[4:5], v[138:139], v[14:15]
	v_add_f32_e32 v44, v14, v15
	v_add_f32_dpp v12, v12, v12 quad_perm:[1,0,3,2] row_mask:0xf bank_mask:0xf bound_ctrl:1
	v_add_f32_dpp v100, v100, v100 row_mirror row_mask:0xf bank_mask:0x3 bound_ctrl:1
	v_add_f32_dpp v100, v44, v44 row_mirror row_mask:0xf bank_mask:0xc bound_ctrl:1
	v_add_f32_dpp v12, v12, v12 quad_perm:[2,3,0,1] row_mask:0xf bank_mask:0xf bound_ctrl:1
	v_pk_mul_f32 v[6:7], v[152:153], v[164:165] op_sel_hi:[1,0]
	v_pk_mul_f32 v[8:9], v[154:155], v[164:165] op_sel_hi:[1,0]
	v_add_f32_dpp v12, v12, v12 row_half_mirror row_mask:0xf bank_mask:0xf bound_ctrl:1
	v_pk_fma_f32 v[6:7], v[2:3], v[144:145], v[6:7]
	v_pk_fma_f32 v[8:9], v[4:5], v[146:147], v[8:9]
	v_add_f32_dpp v12, v12, v12 row_mirror row_mask:0xf bank_mask:0xf bound_ctrl:1
	ds_read_b128 v[34:37], v84 offset:15552
	ds_read_b128 v[22:25], v84 offset:14784
	ds_read_b128 v[30:33], v84 offset:15296
	ds_read_b32 v42, v83 offset:16064
	ds_read_b128 v[26:29], v84 offset:15040
	ds_read_b128 v[38:41], v84 offset:15808
	v_pk_fma_f32 v[2:3], v[148:149], v[12:13], v[6:7] op_sel_hi:[1,0,1] neg_lo:[0,1,0] neg_hi:[0,1,0]
	v_pk_fma_f32 v[4:5], v[150:151], v[12:13], v[8:9] op_sel_hi:[1,0,1] neg_lo:[0,1,0] neg_hi:[0,1,0]
	s_waitcnt lgkmcnt(6)
	v_pk_mul_f32 v[10:11], v[2:3], v[180:181]
	v_pk_fma_f32 v[10:11], v[4:5], v[182:183], v[10:11]
	v_pk_mul_f32 v[14:15], v[2:3], v[160:161]
	v_add_f32_e32 v12, v10, v11
	v_pk_fma_f32 v[14:15], v[4:5], v[162:163], v[14:15]
	v_add_f32_e32 v44, v14, v15
	v_add_f32_dpp v12, v12, v12 quad_perm:[1,0,3,2] row_mask:0xf bank_mask:0xf bound_ctrl:1
	v_add_f32_dpp v101, v101, v101 row_mirror row_mask:0xf bank_mask:0x3 bound_ctrl:1
	v_add_f32_dpp v101, v44, v44 row_mirror row_mask:0xf bank_mask:0xc bound_ctrl:1
	v_add_f32_dpp v12, v12, v12 quad_perm:[2,3,0,1] row_mask:0xf bank_mask:0xf bound_ctrl:1
	v_pk_mul_f32 v[6:7], v[176:177], v[188:189] op_sel_hi:[1,0]
	v_pk_mul_f32 v[8:9], v[178:179], v[188:189] op_sel_hi:[1,0]
	v_add_f32_dpp v12, v12, v12 row_half_mirror row_mask:0xf bank_mask:0xf bound_ctrl:1
	v_pk_fma_f32 v[6:7], v[2:3], v[168:169], v[6:7]
	v_pk_fma_f32 v[8:9], v[4:5], v[170:171], v[8:9]
	v_add_f32_dpp v12, v12, v12 row_mirror row_mask:0xf bank_mask:0xf bound_ctrl:1
	ds_read_b128 v[132:135], v84 offset:16896
	ds_read_b128 v[120:123], v84 offset:16128
	ds_read_b128 v[128:131], v84 offset:16640
	ds_read_b32 v140, v83 offset:17408
	ds_read_b128 v[124:127], v84 offset:16384
	ds_read_b128 v[136:139], v84 offset:17152
	v_pk_fma_f32 v[2:3], v[172:173], v[12:13], v[6:7] op_sel_hi:[1,0,1] neg_lo:[0,1,0] neg_hi:[0,1,0]
	v_pk_fma_f32 v[4:5], v[174:175], v[12:13], v[8:9] op_sel_hi:[1,0,1] neg_lo:[0,1,0] neg_hi:[0,1,0]
	s_waitcnt lgkmcnt(6)
	v_pk_mul_f32 v[10:11], v[2:3], v[34:35]
	v_pk_fma_f32 v[10:11], v[4:5], v[36:37], v[10:11]
	v_pk_mul_f32 v[14:15], v[2:3], v[184:185]
	v_add_f32_e32 v12, v10, v11
	v_pk_fma_f32 v[14:15], v[4:5], v[186:187], v[14:15]
	v_add_f32_e32 v44, v14, v15
	v_add_f32_dpp v12, v12, v12 quad_perm:[1,0,3,2] row_mask:0xf bank_mask:0xf bound_ctrl:1
	v_add_f32_dpp v102, v102, v102 row_mirror row_mask:0xf bank_mask:0x3 bound_ctrl:1
	v_add_f32_dpp v102, v44, v44 row_mirror row_mask:0xf bank_mask:0xc bound_ctrl:1
	v_add_f32_dpp v12, v12, v12 quad_perm:[2,3,0,1] row_mask:0xf bank_mask:0xf bound_ctrl:1
	v_pk_mul_f32 v[6:7], v[30:31], v[42:43] op_sel_hi:[1,0]
	v_pk_mul_f32 v[8:9], v[32:33], v[42:43] op_sel_hi:[1,0]
	v_add_f32_dpp v12, v12, v12 row_half_mirror row_mask:0xf bank_mask:0xf bound_ctrl:1
	v_pk_fma_f32 v[6:7], v[2:3], v[22:23], v[6:7]
	v_pk_fma_f32 v[8:9], v[4:5], v[24:25], v[8:9]
	v_add_f32_dpp v12, v12, v12 row_mirror row_mask:0xf bank_mask:0xf bound_ctrl:1
	ds_read_b128 v[156:159], v84 offset:18240
	ds_read_b128 v[144:147], v84 offset:17472
	ds_read_b128 v[152:155], v84 offset:17984
	ds_read_b32 v164, v83 offset:18752
	ds_read_b128 v[148:151], v84 offset:17728
	ds_read_b128 v[160:163], v84 offset:18496
	v_pk_fma_f32 v[2:3], v[26:27], v[12:13], v[6:7] op_sel_hi:[1,0,1] neg_lo:[0,1,0] neg_hi:[0,1,0]
	v_pk_fma_f32 v[4:5], v[28:29], v[12:13], v[8:9] op_sel_hi:[1,0,1] neg_lo:[0,1,0] neg_hi:[0,1,0]
	s_waitcnt lgkmcnt(6)
; #define LAS __attribute__((address_space(3)))
; template <int CTRL> __device__ __forceinline__ float dpp_f(float v) { return __int_as_float(__builtin_amdgcn_update_dpp(0, __float_as_int(v), CTRL, 0xf, 0xf, true)); }
; __device__ __forceinline__ float row16_sum(float v) { v += dpp_f<0xB1>(v); v += dpp_f<0x4E>(v); v += dpp_f<0x141>(v); v += dpp_f<0x140>(v); return v; }
; __device__ __forceinline__ float tr16_sum(const float (&p)[16], int kq) {
;     const bool b3 = (kq & 8) != 0, b2 = (kq & 4) != 0, b1 = (kq & 2) != 0, b0 = (kq & 1) != 0;
;     float q[8], r[4], u[2];
; #pragma unroll
;     for (int t = 0; t < 8; ++t) { const float keep = b3 ? p[t + 8] : p[t], send = b3 ? p[t] : p[t + 8]; q[t] = keep + dpp_f<0x140>(send); }
; #pragma unroll
;     for (int t = 0; t < 4; ++t) { const float keep = b2 ? q[t + 4] : q[t], send = b2 ? q[t] : q[t + 4]; r[t] = keep + dpp_f<0x141>(send); }
; #pragma unroll
;     for (int t = 0; t < 2; ++t) { const float keep = b1 ? r[t + 2] : r[t], send = b1 ? r[t] : r[t + 2]; u[t] = keep + dpp_f<0x4E>(send); }
;     const float keep = b0 ? u[1] : u[0], send = b0 ? u[0] : u[1];
;     return keep + dpp_f<0xB1>(send);
; __device__ __forceinline__ void rwkv_scan_unit(LAS unsigned char* lds, const float* Wd, const float* V, const bf16_t* RKKB, float* Yraw, int p, int rg, int tid) {
;     ...
;             for (int st = 0; st < SCAN_CH; ++st) {
;                 f32x4 wn = w, bn = b, kn = k, kkn = kk, rn = r; float vn = v;
;                 if (st + 1 < SCAN_CH) { const int o = (st + 1) * SCAN_STEP_B;
;                     wn = *(LAS const f32x4*)(sl + o); bn = *(LAS const f32x4*)(sl + o + 256); kn = *(LAS const f32x4*)(sl + o + 512); kkn = *(LAS const f32x4*)(sl + o + 768); rn = *(LAS const f32x4*)(sl + o + 1024);
;                     vn = *(LAS const float*)(vl + o); }
;                 float sa = (S[0] * kk[0] + S[1] * kk[1]) + (S[2] * kk[2] + S[3] * kk[3]);
;                 const f32x4 kvt = k * v;
;                 sa = -row16_sum(sa);
;                 S = S * w + (b * sa + kvt);
;                 yp[st & 15] = (S[0] * r[0] + S[1] * r[1]) + (S[2] * r[2] + S[3] * r[3]);
;                 if ((st & 15) == 15) yo[(size_t)(st - 15) * 64] = tr16_sum(yp, kq);
;                 w = wn; b = bn; k = kn; kk = kkn; r = rn; v = vn;
	v_pk_mul_f32 v[10:11], v[2:3], v[132:133]
	v_pk_fma_f32 v[10:11], v[4:5], v[134:135], v[10:11]
	v_pk_mul_f32 v[14:15], v[2:3], v[38:39]
	v_add_f32_e32 v12, v10, v11
	v_pk_fma_f32 v[14:15], v[4:5], v[40:41], v[14:15]
	v_add_f32_e32 v44, v14, v15
	v_add_f32_dpp v12, v12, v12 quad_perm:[1,0,3,2] row_mask:0xf bank_mask:0xf bound_ctrl:1
	v_add_f32_dpp v103, v103, v103 row_mirror row_mask:0xf bank_mask:0x3 bound_ctrl:1
	v_add_f32_dpp v103, v44, v44 row_mirror row_mask:0xf bank_mask:0xc bound_ctrl:1
	v_add_f32_dpp v12, v12, v12 quad_perm:[2,3,0,1] row_mask:0xf bank_mask:0xf bound_ctrl:1
	v_pk_mul_f32 v[6:7], v[128:129], v[140:141] op_sel_hi:[1,0]
	v_pk_mul_f32 v[8:9], v[130:131], v[140:141] op_sel_hi:[1,0]
	v_add_f32_dpp v12, v12, v12 row_half_mirror row_mask:0xf bank_mask:0xf bound_ctrl:1
	v_pk_fma_f32 v[6:7], v[2:3], v[120:121], v[6:7]
	v_pk_fma_f32 v[8:9], v[4:5], v[122:123], v[8:9]
	v_add_f32_dpp v12, v12, v12 row_mirror row_mask:0xf bank_mask:0xf bound_ctrl:1
	ds_read_b128 v[180:183], v84 offset:19584
	ds_read_b128 v[168:171], v84 offset:18816
	ds_read_b128 v[176:179], v84 offset:19328
	ds_read_b32 v188, v83 offset:20096
	ds_read_b128 v[172:175], v84 offset:19072
	ds_read_b128 v[184:187], v84 offset:19840
	v_pk_fma_f32 v[2:3], v[124:125], v[12:13], v[6:7] op_sel_hi:[1,0,1] neg_lo:[0,1,0] neg_hi:[0,1,0]
	v_pk_fma_f32 v[4:5], v[126:127], v[12:13], v[8:9] op_sel_hi:[1,0,1] neg_lo:[0,1,0] neg_hi:[0,1,0]
	s_waitcnt lgkmcnt(6)
	v_pk_mul_f32 v[10:11], v[2:3], v[156:157]
	v_pk_fma_f32 v[10:11], v[4:5], v[158:159], v[10:11]
	v_pk_mul_f32 v[14:15], v[2:3], v[136:137]
	v_add_f32_e32 v12, v10, v11
	v_pk_fma_f32 v[14:15], v[4:5], v[138:139], v[14:15]
	v_add_f32_e32 v44, v14, v15
	v_add_f32_dpp v12, v12, v12 quad_perm:[1,0,3,2] row_mask:0xf bank_mask:0xf bound_ctrl:1
	v_add_f32_dpp v104, v104, v104 row_mirror row_mask:0xf bank_mask:0x3 bound_ctrl:1
	v_add_f32_dpp v104, v44, v44 row_mirror row_mask:0xf bank_mask:0xc bound_ctrl:1
	v_add_f32_dpp v12, v12, v12 quad_perm:[2,3,0,1] row_mask:0xf bank_mask:0xf bound_ctrl:1
	v_pk_mul_f32 v[6:7], v[152:153], v[164:165] op_sel_hi:[1,0]
	v_pk_mul_f32 v[8:9], v[154:155], v[164:165] op_sel_hi:[1,0]
	v_add_f32_dpp v12, v12, v12 row_half_mirror row_mask:0xf bank_mask:0xf bound_ctrl:1
	v_pk_fma_f32 v[6:7], v[2:3], v[144:145], v[6:7]
	v_pk_fma_f32 v[8:9], v[4:5], v[146:147], v[8:9]
	v_add_f32_dpp v12, v12, v12 row_mirror row_mask:0xf bank_mask:0xf bound_ctrl:1
	ds_read_b128 v[34:37], v84 offset:20928
	ds_read_b128 v[22:25], v84 offset:20160
	ds_read_b128 v[30:33], v84 offset:20672
	ds_read_b32 v42, v83 offset:21440
	ds_read_b128 v[26:29], v84 offset:20416
	ds_read_b128 v[38:41], v84 offset:21184
	v_pk_fma_f32 v[2:3], v[148:149], v[12:13], v[6:7] op_sel_hi:[1,0,1] neg_lo:[0,1,0] neg_hi:[0,1,0]
	v_pk_fma_f32 v[4:5], v[150:151], v[12:13], v[8:9] op_sel_hi:[1,0,1] neg_lo:[0,1,0] neg_hi:[0,1,0]
	s_waitcnt lgkmcnt(6)
	v_pk_mul_f32 v[10:11], v[2:3], v[180:181]
	v_pk_fma_f32 v[10:11], v[4:5], v[182:183], v[10:11]
	v_pk_mul_f32 v[14:15], v[2:3], v[160:161]
	v_add_f32_e32 v12, v10, v11
	v_pk_fma_f32 v[14:15], v[4:5], v[162:163], v[14:15]
	v_add_f32_e32 v44, v14, v15
	v_add_f32_dpp v12, v12, v12 quad_perm:[1,0,3,2] row_mask:0xf bank_mask:0xf bound_ctrl:1
	v_add_f32_dpp v105, v105, v105 row_mirror row_mask:0xf bank_mask:0x3 bound_ctrl:1
	v_add_f32_dpp v105, v44, v44 row_mirror row_mask:0xf bank_mask:0xc bound_ctrl:1
	v_add_f32_dpp v12, v12, v12 quad_perm:[2,3,0,1] row_mask:0xf bank_mask:0xf bound_ctrl:1
	v_pk_mul_f32 v[6:7], v[176:177], v[188:189] op_sel_hi:[1,0]
	v_pk_mul_f32 v[8:9], v[178:179], v[188:189] op_sel_hi:[1,0]
	v_add_f32_dpp v12, v12, v12 row_half_mirror row_mask:0xf bank_mask:0xf bound_ctrl:1
	v_pk_fma_f32 v[6:7], v[2:3], v[168:169], v[6:7]
	v_pk_fma_f32 v[8:9], v[4:5], v[170:171], v[8:9]
	v_add_f32_dpp v12, v12, v12 row_mirror row_mask:0xf bank_mask:0xf bound_ctrl:1
	ds_read_b128 v[132:135], v84 offset:22272
	ds_read_b128 v[120:123], v84 offset:21504
	ds_read_b128 v[128:131], v84 offset:22016
	ds_read_b32 v140, v83 offset:22784
	ds_read_b128 v[124:127], v84 offset:21760
	ds_read_b128 v[136:139], v84 offset:22528
	v_pk_fma_f32 v[2:3], v[172:173], v[12:13], v[6:7] op_sel_hi:[1,0,1] neg_lo:[0,1,0] neg_hi:[0,1,0]
	v_pk_fma_f32 v[4:5], v[174:175], v[12:13], v[8:9] op_sel_hi:[1,0,1] neg_lo:[0,1,0] neg_hi:[0,1,0]
	s_waitcnt lgkmcnt(6)
	v_pk_mul_f32 v[10:11], v[2:3], v[34:35]
	v_pk_fma_f32 v[10:11], v[4:5], v[36:37], v[10:11]
	v_pk_mul_f32 v[14:15], v[2:3], v[184:185]
	v_add_f32_e32 v12, v10, v11
	v_pk_fma_f32 v[14:15], v[4:5], v[186:187], v[14:15]
	v_add_f32_e32 v44, v14, v15
	v_add_f32_dpp v12, v12, v12 quad_perm:[1,0,3,2] row_mask:0xf bank_mask:0xf bound_ctrl:1
	v_add_f32_dpp v106, v106, v106 row_mirror row_mask:0xf bank_mask:0x3 bound_ctrl:1
	v_add_f32_dpp v106, v44, v44 row_mirror row_mask:0xf bank_mask:0xc bound_ctrl:1
	v_add_f32_dpp v12, v12, v12 quad_perm:[2,3,0,1] row_mask:0xf bank_mask:0xf bound_ctrl:1
	v_pk_mul_f32 v[6:7], v[30:31], v[42:43] op_sel_hi:[1,0]
	v_pk_mul_f32 v[8:9], v[32:33], v[42:43] op_sel_hi:[1,0]
	v_add_f32_dpp v12, v12, v12 row_half_mirror row_mask:0xf bank_mask:0xf bound_ctrl:1
	v_pk_fma_f32 v[6:7], v[2:3], v[22:23], v[6:7]
	v_pk_fma_f32 v[8:9], v[4:5], v[24:25], v[8:9]
	v_add_f32_dpp v12, v12, v12 row_mirror row_mask:0xf bank_mask:0xf bound_ctrl:1
	ds_read_b128 v[156:159], v84 offset:23616
	ds_read_b128 v[144:147], v84 offset:22848
	ds_read_b128 v[152:155], v84 offset:23360
	ds_read_b32 v164, v83 offset:24128
	ds_read_b128 v[148:151], v84 offset:23104
	ds_read_b128 v[160:163], v84 offset:23872
	v_pk_fma_f32 v[2:3], v[26:27], v[12:13], v[6:7] op_sel_hi:[1,0,1] neg_lo:[0,1,0] neg_hi:[0,1,0]
	v_pk_fma_f32 v[4:5], v[28:29], v[12:13], v[8:9] op_sel_hi:[1,0,1] neg_lo:[0,1,0] neg_hi:[0,1,0]
	s_waitcnt lgkmcnt(6)
; #define LAS __attribute__((address_space(3)))
; template <int CTRL> __device__ __forceinline__ float dpp_f(float v) { return __int_as_float(__builtin_amdgcn_update_dpp(0, __float_as_int(v), CTRL, 0xf, 0xf, true)); }
; __device__ __forceinline__ float row16_sum(float v) { v += dpp_f<0xB1>(v); v += dpp_f<0x4E>(v); v += dpp_f<0x141>(v); v += dpp_f<0x140>(v); return v; }
; __device__ __forceinline__ float tr16_sum(const float (&p)[16], int kq) {
;     const bool b3 = (kq & 8) != 0, b2 = (kq & 4) != 0, b1 = (kq & 2) != 0, b0 = (kq & 1) != 0;
;     float q[8], r[4], u[2];
; #pragma unroll
;     for (int t = 0; t < 8; ++t) { const float keep = b3 ? p[t + 8] : p[t], send = b3 ? p[t] : p[t + 8]; q[t] = keep + dpp_f<0x140>(send); }
; #pragma unroll
;     for (int t = 0; t < 4; ++t) { const float keep = b2 ? q[t + 4] : q[t], send = b2 ? q[t] : q[t + 4]; r[t] = keep + dpp_f<0x141>(send); }
; #pragma unroll
;     for (int t = 0; t < 2; ++t) { const float keep = b1 ? r[t + 2] : r[t], send = b1 ? r[t] : r[t + 2]; u[t] = keep + dpp_f<0x4E>(send); }
;     const float keep = b0 ? u[1] : u[0], send = b0 ? u[0] : u[1];
;     return keep + dpp_f<0xB1>(send);
; __device__ __forceinline__ void rwkv_scan_unit(LAS unsigned char* lds, const float* Wd, const float* V, const bf16_t* RKKB, float* Yraw, int p, int rg, int tid) {
;     ...
;             for (int st = 0; st < SCAN_CH; ++st) {
;                 f32x4 wn = w, bn = b, kn = k, kkn = kk, rn = r; float vn = v;
;                 if (st + 1 < SCAN_CH) { const int o = (st + 1) * SCAN_STEP_B;
;                     wn = *(LAS const f32x4*)(sl + o); bn = *(LAS const f32x4*)(sl + o + 256); kn = *(LAS const f32x4*)(sl + o + 512); kkn = *(LAS const f32x4*)(sl + o + 768); rn = *(LAS const f32x4*)(sl + o + 1024);
;                     vn = *(LAS const float*)(vl + o); }
;                 float sa = (S[0] * kk[0] + S[1] * kk[1]) + (S[2] * kk[2] + S[3] * kk[3]);
;                 const f32x4 kvt = k * v;
;                 sa = -row16_sum(sa);
;                 S = S * w + (b * sa + kvt);
;                 yp[st & 15] = (S[0] * r[0] + S[1] * r[1]) + (S[2] * r[2] + S[3] * r[3]);
;                 if ((st & 15) == 15) yo[(size_t)(st - 15) * 64] = tr16_sum(yp, kq);
;                 w = wn; b = bn; k = kn; kk = kkn; r = rn; v = vn;
	v_pk_mul_f32 v[10:11], v[2:3], v[132:133]
	v_pk_fma_f32 v[10:11], v[4:5], v[134:135], v[10:11]
	v_pk_mul_f32 v[14:15], v[2:3], v[38:39]
	v_add_f32_e32 v12, v10, v11
	v_pk_fma_f32 v[14:15], v[4:5], v[40:41], v[14:15]
	v_add_f32_e32 v44, v14, v15
	v_add_f32_dpp v107, v107, v107 row_mirror row_mask:0xf bank_mask:0x3 bound_ctrl:1
	s_nop 0
	v_add_f32_dpp v107, v44, v44 row_mirror row_mask:0xf bank_mask:0xc bound_ctrl:1
	v_add_f32_dpp v12, v12, v12 quad_perm:[1,0,3,2] row_mask:0xf bank_mask:0xf bound_ctrl:1
	v_pk_mul_f32 v[6:7], v[128:129], v[140:141] op_sel_hi:[1,0]
	v_pk_mul_f32 v[8:9], v[130:131], v[140:141] op_sel_hi:[1,0]
	v_pk_fma_f32 v[6:7], v[2:3], v[120:121], v[6:7]
	v_pk_fma_f32 v[8:9], v[4:5], v[122:123], v[8:9]
	v_add_f32_dpp v12, v12, v12 quad_perm:[2,3,0,1] row_mask:0xf bank_mask:0xf bound_ctrl:1
	ds_read_b128 v[180:183], v84 offset:24960
	ds_read_b128 v[168:171], v84 offset:24192
	ds_read_b128 v[176:179], v84 offset:24704
	ds_read_b32 v188, v83 offset:25472
	v_add_f32_dpp v12, v12, v12 row_half_mirror row_mask:0xf bank_mask:0xf bound_ctrl:1
	ds_read_b128 v[172:175], v84 offset:24448
	ds_read_b128 v[184:187], v84 offset:25216
	v_add_f32_dpp v100, v100, v100 row_half_mirror row_mask:0xf bank_mask:0x5 bound_ctrl:1
	v_add_f32_dpp v100, v104, v104 row_half_mirror row_mask:0xf bank_mask:0xa bound_ctrl:1
	v_add_f32_dpp v12, v12, v12 row_mirror row_mask:0xf bank_mask:0xf bound_ctrl:1
	v_add_f32_dpp v101, v101, v101 row_half_mirror row_mask:0xf bank_mask:0x5 bound_ctrl:1
	v_add_f32_dpp v101, v105, v105 row_half_mirror row_mask:0xf bank_mask:0xa bound_ctrl:1
	v_add_f32_dpp v102, v102, v102 row_half_mirror row_mask:0xf bank_mask:0x5 bound_ctrl:1
	v_add_f32_dpp v102, v106, v106 row_half_mirror row_mask:0xf bank_mask:0xa bound_ctrl:1
	v_add_f32_dpp v103, v103, v103 row_half_mirror row_mask:0xf bank_mask:0x5 bound_ctrl:1
	v_add_f32_dpp v103, v107, v107 row_half_mirror row_mask:0xf bank_mask:0xa bound_ctrl:1
	v_pk_fma_f32 v[2:3], v[124:125], v[12:13], v[6:7] op_sel_hi:[1,0,1] neg_lo:[0,1,0] neg_hi:[0,1,0]
	v_pk_fma_f32 v[4:5], v[126:127], v[12:13], v[8:9] op_sel_hi:[1,0,1] neg_lo:[0,1,0] neg_hi:[0,1,0]
	s_waitcnt lgkmcnt(6)
	v_pk_mul_f32 v[10:11], v[2:3], v[156:157]
	v_pk_fma_f32 v[10:11], v[4:5], v[158:159], v[10:11]
	v_pk_mul_f32 v[14:15], v[2:3], v[136:137]
	v_add_f32_e32 v12, v10, v11
	v_pk_fma_f32 v[14:15], v[4:5], v[138:139], v[14:15]
	v_add_f32_e32 v108, v14, v15
	v_pk_mul_f32 v[6:7], v[152:153], v[164:165] op_sel_hi:[1,0]
	v_pk_mul_f32 v[8:9], v[154:155], v[164:165] op_sel_hi:[1,0]
	v_add_f32_dpp v12, v12, v12 quad_perm:[1,0,3,2] row_mask:0xf bank_mask:0xf bound_ctrl:1
	v_pk_fma_f32 v[6:7], v[2:3], v[144:145], v[6:7]
	v_pk_fma_f32 v[8:9], v[4:5], v[146:147], v[8:9]
	ds_read_b128 v[34:37], v84 offset:26304
	ds_read_b128 v[22:25], v84 offset:25536
	v_add_f32_dpp v12, v12, v12 quad_perm:[2,3,0,1] row_mask:0xf bank_mask:0xf bound_ctrl:1
	ds_read_b128 v[30:33], v84 offset:26048
	ds_read_b32 v42, v83 offset:26816
	ds_read_b128 v[26:29], v84 offset:25792
	ds_read_b128 v[38:41], v84 offset:26560
	v_add_f32_dpp v12, v12, v12 row_half_mirror row_mask:0xf bank_mask:0xf bound_ctrl:1
	v_cndmask_b32_e64 v16, v102, v100, s[8:9]
	v_cndmask_b32_e64 v17, v100, v102, s[8:9]
	s_nop 1
	v_add_f32_dpp v16, v17, v16 quad_perm:[2,3,0,1] row_mask:0xf bank_mask:0xf bound_ctrl:1
	v_cndmask_b32_e64 v18, v103, v101, s[8:9]
	v_add_f32_dpp v12, v12, v12 row_mirror row_mask:0xf bank_mask:0xf bound_ctrl:1
	v_cndmask_b32_e64 v19, v101, v103, s[8:9]
	s_nop 1
	v_add_f32_dpp v18, v19, v18 quad_perm:[2,3,0,1] row_mask:0xf bank_mask:0xf bound_ctrl:1
	v_cndmask_b32_e64 v17, v18, v16, s[10:11]
	v_cndmask_b32_e64 v19, v16, v18, s[10:11]
	s_nop 1
	v_add_f32_dpp v17, v19, v17 quad_perm:[1,0,3,2] row_mask:0xf bank_mask:0xf bound_ctrl:1
	global_store_dword v[88:89], v17, off
	v_pk_fma_f32 v[2:3], v[148:149], v[12:13], v[6:7] op_sel_hi:[1,0,1] neg_lo:[0,1,0] neg_hi:[0,1,0]
	v_pk_fma_f32 v[4:5], v[150:151], v[12:13], v[8:9] op_sel_hi:[1,0,1] neg_lo:[0,1,0] neg_hi:[0,1,0]
	s_waitcnt lgkmcnt(6)
	v_pk_mul_f32 v[10:11], v[2:3], v[180:181]
	v_pk_fma_f32 v[10:11], v[4:5], v[182:183], v[10:11]
	v_pk_mul_f32 v[14:15], v[2:3], v[160:161]
	v_add_f32_e32 v12, v10, v11
	v_pk_fma_f32 v[14:15], v[4:5], v[162:163], v[14:15]
	v_add_f32_e32 v109, v14, v15
	v_add_f32_dpp v12, v12, v12 quad_perm:[1,0,3,2] row_mask:0xf bank_mask:0xf bound_ctrl:1
	v_pk_mul_f32 v[6:7], v[176:177], v[188:189] op_sel_hi:[1,0]
	v_pk_mul_f32 v[8:9], v[178:179], v[188:189] op_sel_hi:[1,0]
	v_add_f32_dpp v12, v12, v12 quad_perm:[2,3,0,1] row_mask:0xf bank_mask:0xf bound_ctrl:1
	v_pk_fma_f32 v[6:7], v[2:3], v[168:169], v[6:7]
	v_pk_fma_f32 v[8:9], v[4:5], v[170:171], v[8:9]
	v_add_f32_dpp v12, v12, v12 row_half_mirror row_mask:0xf bank_mask:0xf bound_ctrl:1
	ds_read_b128 v[132:135], v84 offset:27648
	ds_read_b128 v[120:123], v84 offset:26880
	v_add_f32_dpp v12, v12, v12 row_mirror row_mask:0xf bank_mask:0xf bound_ctrl:1
	ds_read_b128 v[128:131], v84 offset:27392
	ds_read_b32 v140, v83 offset:28160
	ds_read_b128 v[124:127], v84 offset:27136
	ds_read_b128 v[136:139], v84 offset:27904
	v_pk_fma_f32 v[2:3], v[172:173], v[12:13], v[6:7] op_sel_hi:[1,0,1] neg_lo:[0,1,0] neg_hi:[0,1,0]
	v_pk_fma_f32 v[4:5], v[174:175], v[12:13], v[8:9] op_sel_hi:[1,0,1] neg_lo:[0,1,0] neg_hi:[0,1,0]
	s_waitcnt lgkmcnt(6)
; #define LAS __attribute__((address_space(3)))
; __device__ __forceinline__ float row16_sum(float v) { v += dpp_f<0xB1>(v); v += dpp_f<0x4E>(v); v += dpp_f<0x141>(v); v += dpp_f<0x140>(v); return v; }
; __device__ __forceinline__ void rwkv_scan_unit(LAS unsigned char* lds, const float* Wd, const float* V, const bf16_t* RKKB, float* Yraw, int p, int rg, int tid) {
;     ...
;             for (int st = 0; st < SCAN_CH; ++st) {
;                 f32x4 wn = w, bn = b, kn = k, kkn = kk, rn = r; float vn = v;
;                 if (st + 1 < SCAN_CH) { const int o = (st + 1) * SCAN_STEP_B;
;                     wn = *(LAS const f32x4*)(sl + o); bn = *(LAS const f32x4*)(sl + o + 256); kn = *(LAS const f32x4*)(sl + o + 512); kkn = *(LAS const f32x4*)(sl + o + 768); rn = *(LAS const f32x4*)(sl + o + 1024);
;                     vn = *(LAS const float*)(vl + o); }
;                 float sa = (S[0] * kk[0] + S[1] * kk[1]) + (S[2] * kk[2] + S[3] * kk[3]);
;                 const f32x4 kvt = k * v;
;                 sa = -row16_sum(sa);
;                 S = S * w + (b * sa + kvt);
;                 yp[st & 15] = (S[0] * r[0] + S[1] * r[1]) + (S[2] * r[2] + S[3] * r[3]);
;                 if ((st & 15) == 15) yo[(size_t)(st - 15) * 64] = tr16_sum(yp, kq);
;                 w = wn; b = bn; k = kn; kk = kkn; r = rn; v = vn;
	v_pk_mul_f32 v[10:11], v[2:3], v[34:35]
	v_pk_fma_f32 v[10:11], v[4:5], v[36:37], v[10:11]
	v_pk_mul_f32 v[14:15], v[2:3], v[184:185]
	v_add_f32_e32 v12, v10, v11
	v_pk_fma_f32 v[14:15], v[4:5], v[186:187], v[14:15]
	v_add_f32_e32 v110, v14, v15
	v_add_f32_dpp v12, v12, v12 quad_perm:[1,0,3,2] row_mask:0xf bank_mask:0xf bound_ctrl:1
	v_pk_mul_f32 v[6:7], v[30:31], v[42:43] op_sel_hi:[1,0]
	v_pk_mul_f32 v[8:9], v[32:33], v[42:43] op_sel_hi:[1,0]
	v_add_f32_dpp v12, v12, v12 quad_perm:[2,3,0,1] row_mask:0xf bank_mask:0xf bound_ctrl:1
	v_pk_fma_f32 v[6:7], v[2:3], v[22:23], v[6:7]
	v_pk_fma_f32 v[8:9], v[4:5], v[24:25], v[8:9]
	v_add_f32_dpp v12, v12, v12 row_half_mirror row_mask:0xf bank_mask:0xf bound_ctrl:1
	ds_read_b128 v[156:159], v84 offset:28992
	ds_read_b128 v[144:147], v84 offset:28224
	v_add_f32_dpp v12, v12, v12 row_mirror row_mask:0xf bank_mask:0xf bound_ctrl:1
	ds_read_b128 v[152:155], v84 offset:28736
	ds_read_b32 v164, v83 offset:29504
	ds_read_b128 v[148:151], v84 offset:28480
	ds_read_b128 v[160:163], v84 offset:29248
	v_pk_fma_f32 v[2:3], v[26:27], v[12:13], v[6:7] op_sel_hi:[1,0,1] neg_lo:[0,1,0] neg_hi:[0,1,0]
	v_pk_fma_f32 v[4:5], v[28:29], v[12:13], v[8:9] op_sel_hi:[1,0,1] neg_lo:[0,1,0] neg_hi:[0,1,0]
	s_waitcnt lgkmcnt(6)
	v_pk_mul_f32 v[10:11], v[2:3], v[132:133]
	v_pk_fma_f32 v[10:11], v[4:5], v[134:135], v[10:11]
	v_pk_mul_f32 v[14:15], v[2:3], v[38:39]
	v_add_f32_e32 v12, v10, v11
	v_pk_fma_f32 v[14:15], v[4:5], v[40:41], v[14:15]
	v_add_f32_e32 v111, v14, v15
	v_add_f32_dpp v12, v12, v12 quad_perm:[1,0,3,2] row_mask:0xf bank_mask:0xf bound_ctrl:1
	v_pk_mul_f32 v[6:7], v[128:129], v[140:141] op_sel_hi:[1,0]
	v_pk_mul_f32 v[8:9], v[130:131], v[140:141] op_sel_hi:[1,0]
	v_add_f32_dpp v12, v12, v12 quad_perm:[2,3,0,1] row_mask:0xf bank_mask:0xf bound_ctrl:1
	v_pk_fma_f32 v[6:7], v[2:3], v[120:121], v[6:7]
	v_pk_fma_f32 v[8:9], v[4:5], v[122:123], v[8:9]
	v_add_f32_dpp v12, v12, v12 row_half_mirror row_mask:0xf bank_mask:0xf bound_ctrl:1
	ds_read_b128 v[180:183], v84 offset:30336
	ds_read_b128 v[168:171], v84 offset:29568
	v_add_f32_dpp v12, v12, v12 row_mirror row_mask:0xf bank_mask:0xf bound_ctrl:1
	ds_read_b128 v[176:179], v84 offset:30080
	ds_read_b32 v188, v83 offset:30848
	ds_read_b128 v[172:175], v84 offset:29824
	ds_read_b128 v[184:187], v84 offset:30592
	v_pk_fma_f32 v[2:3], v[124:125], v[12:13], v[6:7] op_sel_hi:[1,0,1] neg_lo:[0,1,0] neg_hi:[0,1,0]
	v_pk_fma_f32 v[4:5], v[126:127], v[12:13], v[8:9] op_sel_hi:[1,0,1] neg_lo:[0,1,0] neg_hi:[0,1,0]
	s_waitcnt lgkmcnt(6)
	v_pk_mul_f32 v[10:11], v[2:3], v[156:157]
	v_pk_fma_f32 v[10:11], v[4:5], v[158:159], v[10:11]
	v_pk_mul_f32 v[14:15], v[2:3], v[136:137]
	v_add_f32_e32 v12, v10, v11
	v_pk_fma_f32 v[14:15], v[4:5], v[138:139], v[14:15]
	v_add_f32_e32 v112, v14, v15
	v_add_f32_dpp v12, v12, v12 quad_perm:[1,0,3,2] row_mask:0xf bank_mask:0xf bound_ctrl:1
	v_pk_mul_f32 v[6:7], v[152:153], v[164:165] op_sel_hi:[1,0]
	v_pk_mul_f32 v[8:9], v[154:155], v[164:165] op_sel_hi:[1,0]
	v_add_f32_dpp v12, v12, v12 quad_perm:[2,3,0,1] row_mask:0xf bank_mask:0xf bound_ctrl:1
	v_pk_fma_f32 v[6:7], v[2:3], v[144:145], v[6:7]
	v_pk_fma_f32 v[8:9], v[4:5], v[146:147], v[8:9]
	v_add_f32_dpp v12, v12, v12 row_half_mirror row_mask:0xf bank_mask:0xf bound_ctrl:1
	ds_read_b128 v[34:37], v84 offset:31680
	ds_read_b128 v[22:25], v84 offset:30912
	v_add_f32_dpp v12, v12, v12 row_mirror row_mask:0xf bank_mask:0xf bound_ctrl:1
	ds_read_b128 v[30:33], v84 offset:31424
	ds_read_b32 v42, v83 offset:32192
	ds_read_b128 v[26:29], v84 offset:31168
	ds_read_b128 v[38:41], v84 offset:31936
	v_pk_fma_f32 v[2:3], v[148:149], v[12:13], v[6:7] op_sel_hi:[1,0,1] neg_lo:[0,1,0] neg_hi:[0,1,0]
	v_pk_fma_f32 v[4:5], v[150:151], v[12:13], v[8:9] op_sel_hi:[1,0,1] neg_lo:[0,1,0] neg_hi:[0,1,0]
	s_waitcnt lgkmcnt(6)
	v_pk_mul_f32 v[10:11], v[2:3], v[180:181]
	v_pk_fma_f32 v[10:11], v[4:5], v[182:183], v[10:11]
	v_pk_mul_f32 v[14:15], v[2:3], v[160:161]
	v_add_f32_e32 v12, v10, v11
	v_pk_fma_f32 v[14:15], v[4:5], v[162:163], v[14:15]
	v_add_f32_e32 v113, v14, v15
	v_add_f32_dpp v12, v12, v12 quad_perm:[1,0,3,2] row_mask:0xf bank_mask:0xf bound_ctrl:1
	v_pk_mul_f32 v[6:7], v[176:177], v[188:189] op_sel_hi:[1,0]
	v_pk_mul_f32 v[8:9], v[178:179], v[188:189] op_sel_hi:[1,0]
	v_add_f32_dpp v12, v12, v12 quad_perm:[2,3,0,1] row_mask:0xf bank_mask:0xf bound_ctrl:1
	v_pk_fma_f32 v[6:7], v[2:3], v[168:169], v[6:7]
	v_pk_fma_f32 v[8:9], v[4:5], v[170:171], v[8:9]
	v_add_f32_dpp v12, v12, v12 row_half_mirror row_mask:0xf bank_mask:0xf bound_ctrl:1
	ds_read_b128 v[132:135], v84 offset:33024
	ds_read_b128 v[120:123], v84 offset:32256
	v_add_f32_dpp v12, v12, v12 row_mirror row_mask:0xf bank_mask:0xf bound_ctrl:1
	ds_read_b128 v[128:131], v84 offset:32768
	ds_read_b32 v140, v83 offset:33536
	ds_read_b128 v[124:127], v84 offset:32512
	ds_read_b128 v[136:139], v84 offset:33280
	v_pk_fma_f32 v[2:3], v[172:173], v[12:13], v[6:7] op_sel_hi:[1,0,1] neg_lo:[0,1,0] neg_hi:[0,1,0]
	v_pk_fma_f32 v[4:5], v[174:175], v[12:13], v[8:9] op_sel_hi:[1,0,1] neg_lo:[0,1,0] neg_hi:[0,1,0]
	s_waitcnt lgkmcnt(6)
; #define LAS __attribute__((address_space(3)))
; template <int CTRL> __device__ __forceinline__ float dpp_f(float v) { return __int_as_float(__builtin_amdgcn_update_dpp(0, __float_as_int(v), CTRL, 0xf, 0xf, true)); }
; __device__ __forceinline__ float row16_sum(float v) { v += dpp_f<0xB1>(v); v += dpp_f<0x4E>(v); v += dpp_f<0x141>(v); v += dpp_f<0x140>(v); return v; }
; __device__ __forceinline__ float tr16_sum(const float (&p)[16], int kq) {
;     const bool b3 = (kq & 8) != 0, b2 = (kq & 4) != 0, b1 = (kq & 2) != 0, b0 = (kq & 1) != 0;
;     float q[8], r[4], u[2];
; #pragma unroll
;     for (int t = 0; t < 8; ++t) { const float keep = b3 ? p[t + 8] : p[t], send = b3 ? p[t] : p[t + 8]; q[t] = keep + dpp_f<0x140>(send); }
; #pragma unroll
;     for (int t = 0; t < 4; ++t) { const float keep = b2 ? q[t + 4] : q[t], send = b2 ? q[t] : q[t + 4]; r[t] = keep + dpp_f<0x141>(send); }
; #pragma unroll
;     for (int t = 0; t < 2; ++t) { const float keep = b1 ? r[t + 2] : r[t], send = b1 ? r[t] : r[t + 2]; u[t] = keep + dpp_f<0x4E>(send); }
;     const float keep = b0 ? u[1] : u[0], send = b0 ? u[0] : u[1];
;     return keep + dpp_f<0xB1>(send);
; __device__ __forceinline__ void rwkv_scan_unit(LAS unsigned char* lds, const float* Wd, const float* V, const bf16_t* RKKB, float* Yraw, int p, int rg, int tid) {
;     ...
;             for (int st = 0; st < SCAN_CH; ++st) {
;                 f32x4 wn = w, bn = b, kn = k, kkn = kk, rn = r; float vn = v;
;                 if (st + 1 < SCAN_CH) { const int o = (st + 1) * SCAN_STEP_B;
;                     wn = *(LAS const f32x4*)(sl + o); bn = *(LAS const f32x4*)(sl + o + 256); kn = *(LAS const f32x4*)(sl + o + 512); kkn = *(LAS const f32x4*)(sl + o + 768); rn = *(LAS const f32x4*)(sl + o + 1024);
;                     vn = *(LAS const float*)(vl + o); }
;                 float sa = (S[0] * kk[0] + S[1] * kk[1]) + (S[2] * kk[2] + S[3] * kk[3]);
;                 const f32x4 kvt = k * v;
;                 sa = -row16_sum(sa);
;                 S = S * w + (b * sa + kvt);
;                 yp[st & 15] = (S[0] * r[0] + S[1] * r[1]) + (S[2] * r[2] + S[3] * r[3]);
;                 if ((st & 15) == 15) yo[(size_t)(st - 15) * 64] = tr16_sum(yp, kq);
;                 w = wn; b = bn; k = kn; kk = kkn; r = rn; v = vn;
	v_pk_mul_f32 v[10:11], v[2:3], v[34:35]
	v_pk_fma_f32 v[10:11], v[4:5], v[36:37], v[10:11]
	v_pk_mul_f32 v[14:15], v[2:3], v[184:185]
	v_add_f32_e32 v12, v10, v11
	v_pk_fma_f32 v[14:15], v[4:5], v[186:187], v[14:15]
	v_add_f32_e32 v114, v14, v15
	v_add_f32_dpp v12, v12, v12 quad_perm:[1,0,3,2] row_mask:0xf bank_mask:0xf bound_ctrl:1
	v_pk_mul_f32 v[6:7], v[30:31], v[42:43] op_sel_hi:[1,0]
	v_pk_mul_f32 v[8:9], v[32:33], v[42:43] op_sel_hi:[1,0]
	v_add_f32_dpp v12, v12, v12 quad_perm:[2,3,0,1] row_mask:0xf bank_mask:0xf bound_ctrl:1
	v_pk_fma_f32 v[6:7], v[2:3], v[22:23], v[6:7]
	v_pk_fma_f32 v[8:9], v[4:5], v[24:25], v[8:9]
	v_add_f32_dpp v12, v12, v12 row_half_mirror row_mask:0xf bank_mask:0xf bound_ctrl:1
	ds_read_b128 v[156:159], v84 offset:34368
	ds_read_b128 v[144:147], v84 offset:33600
	v_add_f32_dpp v12, v12, v12 row_mirror row_mask:0xf bank_mask:0xf bound_ctrl:1
	ds_read_b128 v[152:155], v84 offset:34112
	ds_read_b32 v164, v83 offset:34880
	ds_read_b128 v[148:151], v84 offset:33856
	ds_read_b128 v[160:163], v84 offset:34624
	v_pk_fma_f32 v[2:3], v[26:27], v[12:13], v[6:7] op_sel_hi:[1,0,1] neg_lo:[0,1,0] neg_hi:[0,1,0]
	v_pk_fma_f32 v[4:5], v[28:29], v[12:13], v[8:9] op_sel_hi:[1,0,1] neg_lo:[0,1,0] neg_hi:[0,1,0]
	s_waitcnt lgkmcnt(6)
	v_pk_mul_f32 v[10:11], v[2:3], v[132:133]
	v_pk_fma_f32 v[10:11], v[4:5], v[134:135], v[10:11]
	v_pk_mul_f32 v[14:15], v[2:3], v[38:39]
	v_add_f32_e32 v12, v10, v11
	v_pk_fma_f32 v[14:15], v[4:5], v[40:41], v[14:15]
	v_add_f32_e32 v115, v14, v15
	v_add_f32_dpp v12, v12, v12 quad_perm:[1,0,3,2] row_mask:0xf bank_mask:0xf bound_ctrl:1
	v_pk_mul_f32 v[6:7], v[128:129], v[140:141] op_sel_hi:[1,0]
	v_pk_mul_f32 v[8:9], v[130:131], v[140:141] op_sel_hi:[1,0]
	v_add_f32_dpp v12, v12, v12 quad_perm:[2,3,0,1] row_mask:0xf bank_mask:0xf bound_ctrl:1
	v_pk_fma_f32 v[6:7], v[2:3], v[120:121], v[6:7]
	v_pk_fma_f32 v[8:9], v[4:5], v[122:123], v[8:9]
	v_add_f32_dpp v12, v12, v12 row_half_mirror row_mask:0xf bank_mask:0xf bound_ctrl:1
	ds_read_b128 v[180:183], v84 offset:35712
	ds_read_b128 v[168:171], v84 offset:34944
	v_add_f32_dpp v12, v12, v12 row_mirror row_mask:0xf bank_mask:0xf bound_ctrl:1
	ds_read_b128 v[176:179], v84 offset:35456
	ds_read_b32 v188, v83 offset:36224
	ds_read_b128 v[172:175], v84 offset:35200
	ds_read_b128 v[184:187], v84 offset:35968
	v_pk_fma_f32 v[2:3], v[124:125], v[12:13], v[6:7] op_sel_hi:[1,0,1] neg_lo:[0,1,0] neg_hi:[0,1,0]
	v_pk_fma_f32 v[4:5], v[126:127], v[12:13], v[8:9] op_sel_hi:[1,0,1] neg_lo:[0,1,0] neg_hi:[0,1,0]
	s_waitcnt lgkmcnt(6)
	v_pk_mul_f32 v[10:11], v[2:3], v[156:157]
	v_pk_fma_f32 v[10:11], v[4:5], v[158:159], v[10:11]
	v_pk_mul_f32 v[14:15], v[2:3], v[136:137]
	v_add_f32_e32 v12, v10, v11
	v_pk_fma_f32 v[14:15], v[4:5], v[138:139], v[14:15]
	v_add_f32_e32 v44, v14, v15
	v_add_f32_dpp v12, v12, v12 quad_perm:[1,0,3,2] row_mask:0xf bank_mask:0xf bound_ctrl:1
	v_add_f32_dpp v108, v108, v108 row_mirror row_mask:0xf bank_mask:0x3 bound_ctrl:1
	v_add_f32_dpp v108, v44, v44 row_mirror row_mask:0xf bank_mask:0xc bound_ctrl:1
	v_add_f32_dpp v12, v12, v12 quad_perm:[2,3,0,1] row_mask:0xf bank_mask:0xf bound_ctrl:1
	v_pk_mul_f32 v[6:7], v[152:153], v[164:165] op_sel_hi:[1,0]
	v_pk_mul_f32 v[8:9], v[154:155], v[164:165] op_sel_hi:[1,0]
	v_add_f32_dpp v12, v12, v12 row_half_mirror row_mask:0xf bank_mask:0xf bound_ctrl:1
	v_pk_fma_f32 v[6:7], v[2:3], v[144:145], v[6:7]
	v_pk_fma_f32 v[8:9], v[4:5], v[146:147], v[8:9]
	v_add_f32_dpp v12, v12, v12 row_mirror row_mask:0xf bank_mask:0xf bound_ctrl:1
	ds_read_b128 v[34:37], v84 offset:37056
	ds_read_b128 v[22:25], v84 offset:36288
	ds_read_b128 v[30:33], v84 offset:36800
	ds_read_b32 v42, v83 offset:37568
	ds_read_b128 v[26:29], v84 offset:36544
	ds_read_b128 v[38:41], v84 offset:37312
	v_pk_fma_f32 v[2:3], v[148:149], v[12:13], v[6:7] op_sel_hi:[1,0,1] neg_lo:[0,1,0] neg_hi:[0,1,0]
	v_pk_fma_f32 v[4:5], v[150:151], v[12:13], v[8:9] op_sel_hi:[1,0,1] neg_lo:[0,1,0] neg_hi:[0,1,0]
	s_waitcnt lgkmcnt(6)
	v_pk_mul_f32 v[10:11], v[2:3], v[180:181]
	v_pk_fma_f32 v[10:11], v[4:5], v[182:183], v[10:11]
	v_pk_mul_f32 v[14:15], v[2:3], v[160:161]
	v_add_f32_e32 v12, v10, v11
	v_pk_fma_f32 v[14:15], v[4:5], v[162:163], v[14:15]
	v_add_f32_e32 v44, v14, v15
	v_add_f32_dpp v12, v12, v12 quad_perm:[1,0,3,2] row_mask:0xf bank_mask:0xf bound_ctrl:1
	v_add_f32_dpp v109, v109, v109 row_mirror row_mask:0xf bank_mask:0x3 bound_ctrl:1
	v_add_f32_dpp v109, v44, v44 row_mirror row_mask:0xf bank_mask:0xc bound_ctrl:1
	v_add_f32_dpp v12, v12, v12 quad_perm:[2,3,0,1] row_mask:0xf bank_mask:0xf bound_ctrl:1
	v_pk_mul_f32 v[6:7], v[176:177], v[188:189] op_sel_hi:[1,0]
	v_pk_mul_f32 v[8:9], v[178:179], v[188:189] op_sel_hi:[1,0]
	v_add_f32_dpp v12, v12, v12 row_half_mirror row_mask:0xf bank_mask:0xf bound_ctrl:1
	v_pk_fma_f32 v[6:7], v[2:3], v[168:169], v[6:7]
	v_pk_fma_f32 v[8:9], v[4:5], v[170:171], v[8:9]
	v_add_f32_dpp v12, v12, v12 row_mirror row_mask:0xf bank_mask:0xf bound_ctrl:1
	ds_read_b128 v[132:135], v84 offset:38400
	ds_read_b128 v[120:123], v84 offset:37632
	ds_read_b128 v[128:131], v84 offset:38144
	ds_read_b32 v140, v83 offset:38912
	ds_read_b128 v[124:127], v84 offset:37888
	ds_read_b128 v[136:139], v84 offset:38656
	v_pk_fma_f32 v[2:3], v[172:173], v[12:13], v[6:7] op_sel_hi:[1,0,1] neg_lo:[0,1,0] neg_hi:[0,1,0]
	v_pk_fma_f32 v[4:5], v[174:175], v[12:13], v[8:9] op_sel_hi:[1,0,1] neg_lo:[0,1,0] neg_hi:[0,1,0]
	s_waitcnt lgkmcnt(6)
; #define LAS __attribute__((address_space(3)))
; template <int CTRL> __device__ __forceinline__ float dpp_f(float v) { return __int_as_float(__builtin_amdgcn_update_dpp(0, __float_as_int(v), CTRL, 0xf, 0xf, true)); }
; __device__ __forceinline__ float row16_sum(float v) { v += dpp_f<0xB1>(v); v += dpp_f<0x4E>(v); v += dpp_f<0x141>(v); v += dpp_f<0x140>(v); return v; }
; __device__ __forceinline__ float tr16_sum(const float (&p)[16], int kq) {
;     const bool b3 = (kq & 8) != 0, b2 = (kq & 4) != 0, b1 = (kq & 2) != 0, b0 = (kq & 1) != 0;
;     float q[8], r[4], u[2];
; #pragma unroll
;     for (int t = 0; t < 8; ++t) { const float keep = b3 ? p[t + 8] : p[t], send = b3 ? p[t] : p[t + 8]; q[t] = keep + dpp_f<0x140>(send); }
; #pragma unroll
;     for (int t = 0; t < 4; ++t) { const float keep = b2 ? q[t + 4] : q[t], send = b2 ? q[t] : q[t + 4]; r[t] = keep + dpp_f<0x141>(send); }
; #pragma unroll
;     for (int t = 0; t < 2; ++t) { const float keep = b1 ? r[t + 2] : r[t], send = b1 ? r[t] : r[t + 2]; u[t] = keep + dpp_f<0x4E>(send); }
;     const float keep = b0 ? u[1] : u[0], send = b0 ? u[0] : u[1];
;     return keep + dpp_f<0xB1>(send);
; __device__ __forceinline__ void rwkv_scan_unit(LAS unsigned char* lds, const float* Wd, const float* V, const bf16_t* RKKB, float* Yraw, int p, int rg, int tid) {
;     ...
;             for (int st = 0; st < SCAN_CH; ++st) {
;                 f32x4 wn = w, bn = b, kn = k, kkn = kk, rn = r; float vn = v;
;                 if (st + 1 < SCAN_CH) { const int o = (st + 1) * SCAN_STEP_B;
;                     wn = *(LAS const f32x4*)(sl + o); bn = *(LAS const f32x4*)(sl + o + 256); kn = *(LAS const f32x4*)(sl + o + 512); kkn = *(LAS const f32x4*)(sl + o + 768); rn = *(LAS const f32x4*)(sl + o + 1024);
;                     vn = *(LAS const float*)(vl + o); }
;                 float sa = (S[0] * kk[0] + S[1] * kk[1]) + (S[2] * kk[2] + S[3] * kk[3]);
;                 const f32x4 kvt = k * v;
;                 sa = -row16_sum(sa);
;                 S = S * w + (b * sa + kvt);
;                 yp[st & 15] = (S[0] * r[0] + S[1] * r[1]) + (S[2] * r[2] + S[3] * r[3]);
;                 if ((st & 15) == 15) yo[(size_t)(st - 15) * 64] = tr16_sum(yp, kq);
;                 w = wn; b = bn; k = kn; kk = kkn; r = rn; v = vn;
	v_pk_mul_f32 v[10:11], v[2:3], v[34:35]
	v_pk_fma_f32 v[10:11], v[4:5], v[36:37], v[10:11]
	v_pk_mul_f32 v[14:15], v[2:3], v[184:185]
	v_add_f32_e32 v12, v10, v11
	v_pk_fma_f32 v[14:15], v[4:5], v[186:187], v[14:15]
	v_add_f32_e32 v44, v14, v15
	v_add_f32_dpp v12, v12, v12 quad_perm:[1,0,3,2] row_mask:0xf bank_mask:0xf bound_ctrl:1
	v_add_f32_dpp v110, v110, v110 row_mirror row_mask:0xf bank_mask:0x3 bound_ctrl:1
	v_add_f32_dpp v110, v44, v44 row_mirror row_mask:0xf bank_mask:0xc bound_ctrl:1
	v_add_f32_dpp v12, v12, v12 quad_perm:[2,3,0,1] row_mask:0xf bank_mask:0xf bound_ctrl:1
	v_pk_mul_f32 v[6:7], v[30:31], v[42:43] op_sel_hi:[1,0]
	v_pk_mul_f32 v[8:9], v[32:33], v[42:43] op_sel_hi:[1,0]
	v_add_f32_dpp v12, v12, v12 row_half_mirror row_mask:0xf bank_mask:0xf bound_ctrl:1
	v_pk_fma_f32 v[6:7], v[2:3], v[22:23], v[6:7]
	v_pk_fma_f32 v[8:9], v[4:5], v[24:25], v[8:9]
	v_add_f32_dpp v12, v12, v12 row_mirror row_mask:0xf bank_mask:0xf bound_ctrl:1
	ds_read_b128 v[156:159], v84 offset:39744
	ds_read_b128 v[144:147], v84 offset:38976
	ds_read_b128 v[152:155], v84 offset:39488
	ds_read_b32 v164, v83 offset:40256
	ds_read_b128 v[148:151], v84 offset:39232
	ds_read_b128 v[160:163], v84 offset:40000
	v_pk_fma_f32 v[2:3], v[26:27], v[12:13], v[6:7] op_sel_hi:[1,0,1] neg_lo:[0,1,0] neg_hi:[0,1,0]
	v_pk_fma_f32 v[4:5], v[28:29], v[12:13], v[8:9] op_sel_hi:[1,0,1] neg_lo:[0,1,0] neg_hi:[0,1,0]
	s_waitcnt lgkmcnt(6)
	v_pk_mul_f32 v[10:11], v[2:3], v[132:133]
	v_pk_fma_f32 v[10:11], v[4:5], v[134:135], v[10:11]
	v_pk_mul_f32 v[14:15], v[2:3], v[38:39]
	v_add_f32_e32 v12, v10, v11
	v_pk_fma_f32 v[14:15], v[4:5], v[40:41], v[14:15]
	v_add_f32_e32 v44, v14, v15
	v_add_f32_dpp v12, v12, v12 quad_perm:[1,0,3,2] row_mask:0xf bank_mask:0xf bound_ctrl:1
	v_add_f32_dpp v111, v111, v111 row_mirror row_mask:0xf bank_mask:0x3 bound_ctrl:1
	v_add_f32_dpp v111, v44, v44 row_mirror row_mask:0xf bank_mask:0xc bound_ctrl:1
	v_add_f32_dpp v12, v12, v12 quad_perm:[2,3,0,1] row_mask:0xf bank_mask:0xf bound_ctrl:1
	v_pk_mul_f32 v[6:7], v[128:129], v[140:141] op_sel_hi:[1,0]
	v_pk_mul_f32 v[8:9], v[130:131], v[140:141] op_sel_hi:[1,0]
	v_add_f32_dpp v12, v12, v12 row_half_mirror row_mask:0xf bank_mask:0xf bound_ctrl:1
	v_pk_fma_f32 v[6:7], v[2:3], v[120:121], v[6:7]
	v_pk_fma_f32 v[8:9], v[4:5], v[122:123], v[8:9]
	v_add_f32_dpp v12, v12, v12 row_mirror row_mask:0xf bank_mask:0xf bound_ctrl:1
	ds_read_b128 v[180:183], v84 offset:41088
	ds_read_b128 v[168:171], v84 offset:40320
	ds_read_b128 v[176:179], v84 offset:40832
	ds_read_b32 v188, v83 offset:41600
	ds_read_b128 v[172:175], v84 offset:40576
	ds_read_b128 v[184:187], v84 offset:41344
	v_pk_fma_f32 v[2:3], v[124:125], v[12:13], v[6:7] op_sel_hi:[1,0,1] neg_lo:[0,1,0] neg_hi:[0,1,0]
	v_pk_fma_f32 v[4:5], v[126:127], v[12:13], v[8:9] op_sel_hi:[1,0,1] neg_lo:[0,1,0] neg_hi:[0,1,0]
	s_waitcnt lgkmcnt(6)
	v_pk_mul_f32 v[10:11], v[2:3], v[156:157]
	v_pk_fma_f32 v[10:11], v[4:5], v[158:159], v[10:11]
	v_pk_mul_f32 v[14:15], v[2:3], v[136:137]
	v_add_f32_e32 v12, v10, v11
	v_pk_fma_f32 v[14:15], v[4:5], v[138:139], v[14:15]
	v_add_f32_e32 v44, v14, v15
	v_add_f32_dpp v12, v12, v12 quad_perm:[1,0,3,2] row_mask:0xf bank_mask:0xf bound_ctrl:1
	v_add_f32_dpp v112, v112, v112 row_mirror row_mask:0xf bank_mask:0x3 bound_ctrl:1
	v_add_f32_dpp v112, v44, v44 row_mirror row_mask:0xf bank_mask:0xc bound_ctrl:1
	v_add_f32_dpp v12, v12, v12 quad_perm:[2,3,0,1] row_mask:0xf bank_mask:0xf bound_ctrl:1
	v_pk_mul_f32 v[6:7], v[152:153], v[164:165] op_sel_hi:[1,0]
	v_pk_mul_f32 v[8:9], v[154:155], v[164:165] op_sel_hi:[1,0]
	v_add_f32_dpp v12, v12, v12 row_half_mirror row_mask:0xf bank_mask:0xf bound_ctrl:1
	v_pk_fma_f32 v[6:7], v[2:3], v[144:145], v[6:7]
	v_pk_fma_f32 v[8:9], v[4:5], v[146:147], v[8:9]
	v_add_f32_dpp v12, v12, v12 row_mirror row_mask:0xf bank_mask:0xf bound_ctrl:1
	ds_read_b128 v[34:37], v84 offset:42432
	ds_read_b128 v[22:25], v84 offset:41664
	ds_read_b128 v[30:33], v84 offset:42176
	ds_read_b32 v42, v83 offset:42944
	ds_read_b128 v[26:29], v84 offset:41920
	ds_read_b128 v[38:41], v84 offset:42688
	v_pk_fma_f32 v[2:3], v[148:149], v[12:13], v[6:7] op_sel_hi:[1,0,1] neg_lo:[0,1,0] neg_hi:[0,1,0]
	v_pk_fma_f32 v[4:5], v[150:151], v[12:13], v[8:9] op_sel_hi:[1,0,1] neg_lo:[0,1,0] neg_hi:[0,1,0]
	s_waitcnt lgkmcnt(6)
; #define LAS __attribute__((address_space(3)))
; __device__ __forceinline__ float tr16_sum(const float (&p)[16], int kq) {
;     const bool b3 = (kq & 8) != 0, b2 = (kq & 4) != 0, b1 = (kq & 2) != 0, b0 = (kq & 1) != 0;
;     float q[8], r[4], u[2];
; #pragma unroll
;     for (int t = 0; t < 8; ++t) { const float keep = b3 ? p[t + 8] : p[t], send = b3 ? p[t] : p[t + 8]; q[t] = keep + dpp_f<0x140>(send); }
; #pragma unroll
; __device__ __forceinline__ void rwkv_scan_unit(LAS unsigned char* lds, const float* Wd, const float* V, const bf16_t* RKKB, float* Yraw, int p, int rg, int tid) {
;     ...
;     for (int c = 0; c < NCH; ++c) {
;         if (wave >= 4) { if (c + 2 < NCH) scan_load_chunk(lds + ((c + 2) % 3) * SCAN_SLOT_B, Wd, V, RKKB, p, rg, (c + 2) * SCAN_CH, tid - 256); }
;         else {
;             LAS const unsigned char* sl = lds + (c % 3) * SCAN_SLOT_B + kq * 16;
;             LAS const unsigned char* vl = lds + (c % 3) * SCAN_SLOT_B + 1280 + rl * 4;
;             float* yo = Yraw + ((size_t)p * SEQ + c * SCAN_CH + kq) * 64 + rg * 16 + rl;
;             f32x4 w = *(LAS const f32x4*)(sl), b = *(LAS const f32x4*)(sl + 256), k = *(LAS const f32x4*)(sl + 512), kk = *(LAS const f32x4*)(sl + 768), r = *(LAS const f32x4*)(sl + 1024);
;             float v = *(LAS const float*)(vl); float yp[16];
; #pragma unroll
;             for (int st = 0; st < SCAN_CH; ++st) {
;                 f32x4 wn = w, bn = b, kn = k, kkn = kk, rn = r; float vn = v;
;                 if (st + 1 < SCAN_CH) { const int o = (st + 1) * SCAN_STEP_B;
;                     wn = *(LAS const f32x4*)(sl + o); bn = *(LAS const f32x4*)(sl + o + 256); kn = *(LAS const f32x4*)(sl + o + 512); kkn = *(LAS const f32x4*)(sl + o + 768); rn = *(LAS const f32x4*)(sl + o + 1024);
;                     vn = *(LAS const float*)(vl + o); }
;                 float sa = (S[0] * kk[0] + S[1] * kk[1]) + (S[2] * kk[2] + S[3] * kk[3]);
;                 const f32x4 kvt = k * v;
;                 sa = -row16_sum(sa);
;                 S = S * w + (b * sa + kvt);
;                 yp[st & 15] = (S[0] * r[0] + S[1] * r[1]) + (S[2] * r[2] + S[3] * r[3]);
;                 if ((st & 15) == 15) yo[(size_t)(st - 15) * 64] = tr16_sum(yp, kq);
;                 w = wn; b = bn; k = kn; kk = kkn; r = rn; v = vn;
;             }
;         }
;         __syncthreads();
;     }
	v_pk_mul_f32 v[10:11], v[2:3], v[180:181]
	v_pk_fma_f32 v[10:11], v[4:5], v[182:183], v[10:11]
	v_pk_mul_f32 v[14:15], v[2:3], v[160:161]
	v_add_f32_e32 v12, v10, v11
	v_pk_fma_f32 v[14:15], v[4:5], v[162:163], v[14:15]
	v_add_f32_e32 v44, v14, v15
	v_add_f32_dpp v12, v12, v12 quad_perm:[1,0,3,2] row_mask:0xf bank_mask:0xf bound_ctrl:1
	v_add_f32_dpp v113, v113, v113 row_mirror row_mask:0xf bank_mask:0x3 bound_ctrl:1
	v_add_f32_dpp v113, v44, v44 row_mirror row_mask:0xf bank_mask:0xc bound_ctrl:1
	v_add_f32_dpp v12, v12, v12 quad_perm:[2,3,0,1] row_mask:0xf bank_mask:0xf bound_ctrl:1
	v_pk_mul_f32 v[6:7], v[176:177], v[188:189] op_sel_hi:[1,0]
	v_pk_mul_f32 v[8:9], v[178:179], v[188:189] op_sel_hi:[1,0]
	v_add_f32_dpp v12, v12, v12 row_half_mirror row_mask:0xf bank_mask:0xf bound_ctrl:1
	v_pk_fma_f32 v[6:7], v[2:3], v[168:169], v[6:7]
	v_pk_fma_f32 v[8:9], v[4:5], v[170:171], v[8:9]
	v_add_f32_dpp v12, v12, v12 row_mirror row_mask:0xf bank_mask:0xf bound_ctrl:1
	ds_read_b128 v[132:135], v86 offset:768
	ds_read_b128 v[120:123], v86
	ds_read_b128 v[128:131], v86 offset:512
	ds_read_b32 v140, v85 offset:1280
	ds_read_b128 v[124:127], v86 offset:256
	ds_read_b128 v[136:139], v86 offset:1024
	v_pk_fma_f32 v[2:3], v[172:173], v[12:13], v[6:7] op_sel_hi:[1,0,1] neg_lo:[0,1,0] neg_hi:[0,1,0]
	v_pk_fma_f32 v[4:5], v[174:175], v[12:13], v[8:9] op_sel_hi:[1,0,1] neg_lo:[0,1,0] neg_hi:[0,1,0]
	s_waitcnt lgkmcnt(6)
	v_pk_mul_f32 v[10:11], v[2:3], v[34:35]
	v_pk_fma_f32 v[10:11], v[4:5], v[36:37], v[10:11]
	v_pk_mul_f32 v[14:15], v[2:3], v[184:185]
	v_add_f32_e32 v12, v10, v11
	v_pk_fma_f32 v[14:15], v[4:5], v[186:187], v[14:15]
	v_add_f32_e32 v44, v14, v15
	v_add_f32_dpp v12, v12, v12 quad_perm:[1,0,3,2] row_mask:0xf bank_mask:0xf bound_ctrl:1
	v_add_f32_dpp v114, v114, v114 row_mirror row_mask:0xf bank_mask:0x3 bound_ctrl:1
	v_add_f32_dpp v114, v44, v44 row_mirror row_mask:0xf bank_mask:0xc bound_ctrl:1
	v_add_f32_dpp v12, v12, v12 quad_perm:[2,3,0,1] row_mask:0xf bank_mask:0xf bound_ctrl:1
	v_pk_mul_f32 v[6:7], v[30:31], v[42:43] op_sel_hi:[1,0]
	v_pk_mul_f32 v[8:9], v[32:33], v[42:43] op_sel_hi:[1,0]
	v_add_f32_dpp v12, v12, v12 row_half_mirror row_mask:0xf bank_mask:0xf bound_ctrl:1
	v_pk_fma_f32 v[6:7], v[2:3], v[22:23], v[6:7]
	v_pk_fma_f32 v[8:9], v[4:5], v[24:25], v[8:9]
	v_add_f32_dpp v12, v12, v12 row_mirror row_mask:0xf bank_mask:0xf bound_ctrl:1
	ds_read_b128 v[156:159], v86 offset:2112
	ds_read_b128 v[144:147], v86 offset:1344
	ds_read_b128 v[152:155], v86 offset:1856
	ds_read_b32 v164, v85 offset:2624
	ds_read_b128 v[148:151], v86 offset:1600
	ds_read_b128 v[160:163], v86 offset:2368
	v_pk_fma_f32 v[2:3], v[26:27], v[12:13], v[6:7] op_sel_hi:[1,0,1] neg_lo:[0,1,0] neg_hi:[0,1,0]
	v_pk_fma_f32 v[4:5], v[28:29], v[12:13], v[8:9] op_sel_hi:[1,0,1] neg_lo:[0,1,0] neg_hi:[0,1,0]
	v_pk_mul_f32 v[14:15], v[2:3], v[38:39]
	v_pk_fma_f32 v[14:15], v[4:5], v[40:41], v[14:15]
	v_add_f32_e32 v44, v14, v15
	v_add_f32_dpp v115, v115, v115 row_mirror row_mask:0xf bank_mask:0x3 bound_ctrl:1
	s_nop 0
	v_add_f32_dpp v115, v44, v44 row_mirror row_mask:0xf bank_mask:0xc bound_ctrl:1
	v_add_f32_dpp v108, v108, v108 row_half_mirror row_mask:0xf bank_mask:0x5 bound_ctrl:1
	v_add_f32_dpp v108, v112, v112 row_half_mirror row_mask:0xf bank_mask:0xa bound_ctrl:1
	v_add_f32_dpp v109, v109, v109 row_half_mirror row_mask:0xf bank_mask:0x5 bound_ctrl:1
	v_add_f32_dpp v109, v113, v113 row_half_mirror row_mask:0xf bank_mask:0xa bound_ctrl:1
	v_add_f32_dpp v110, v110, v110 row_half_mirror row_mask:0xf bank_mask:0x5 bound_ctrl:1
	v_add_f32_dpp v110, v114, v114 row_half_mirror row_mask:0xf bank_mask:0xa bound_ctrl:1
	v_add_f32_dpp v111, v111, v111 row_half_mirror row_mask:0xf bank_mask:0x5 bound_ctrl:1
	v_add_f32_dpp v111, v115, v115 row_half_mirror row_mask:0xf bank_mask:0xa bound_ctrl:1
	v_cndmask_b32_e64 v16, v110, v108, s[8:9]
	v_cndmask_b32_e64 v17, v108, v110, s[8:9]
	s_nop 1
	v_add_f32_dpp v16, v17, v16 quad_perm:[2,3,0,1] row_mask:0xf bank_mask:0xf bound_ctrl:1
	v_cndmask_b32_e64 v18, v111, v109, s[8:9]
	v_cndmask_b32_e64 v19, v109, v111, s[8:9]
	s_nop 1
	v_add_f32_dpp v18, v19, v18 quad_perm:[2,3,0,1] row_mask:0xf bank_mask:0xf bound_ctrl:1
	v_cndmask_b32_e64 v17, v18, v16, s[10:11]
	v_cndmask_b32_e64 v19, v16, v18, s[10:11]
	s_nop 1
	v_add_f32_dpp v17, v19, v17 quad_perm:[1,0,3,2] row_mask:0xf bank_mask:0xf bound_ctrl:1
	global_store_dword v[90:91], v17, off
	s_add_i32 s22, s22, 1
	s_mov_b64 s[18:19], 0x2000
	v_lshl_add_u64 v[60:61], v[60:61], 0, s[18:19]
	s_mov_b64 s[68:69], 0x2000
	s_cmpk_eq_i32 s22, 0x80
	s_barrier
	s_cbranch_scc1 .LBB0_370
	s_branch .Lscan_top
